# stack32 with every per-phase s_setprio flip deleted from the six GEMM main loops (A/B of the template's priority flips)
# speedup vs baseline: 1.0122x; 1.0079x over previous
.LBB0_159:
	ds_read_b128 v[150:153], v147
	ds_read_b128 v[154:157], v147 offset:1024
	ds_read_b128 v[158:161], v147 offset:2048
	ds_read_b128 v[162:165], v147 offset:3072
	ds_read_b128 v[166:169], v148
	ds_read_b128 v[170:173], v148 offset:1024
	ds_read_b128 v[174:177], v148 offset:2048
	ds_read_b128 v[178:181], v148 offset:3072
	s_add_u32 s38, s36, 0x100
	s_addc_u32 s39, s37, 0
	s_cmp_eq_u32 s59, 28
	s_cselect_b32 s43, s19, s39
	s_cselect_b32 s42, s55, s38
	s_cselect_b32 s41, s17, s58
	s_cselect_b32 s40, s56, s57
	v_lshl_add_u64 v[182:183], s[36:37], 0, v[136:137]
	s_add_i32 m0, s35, 0xc000
	s_nop 0
	global_load_lds_dwordx4 v[182:183], off
	v_lshl_add_u64 v[182:183], s[36:37], 0, v[138:139]
	s_add_i32 m0, s35, 0xe000
	s_nop 0
	global_load_lds_dwordx4 v[182:183], off
	ds_read_b128 v[182:185], v149
	ds_read_b128 v[186:189], v149 offset:1024
	ds_read_b128 v[190:193], v149 offset:2048
	ds_read_b128 v[194:197], v149 offset:3072
	ds_read_b128 v[198:201], v149 offset:4096
	ds_read_b128 v[202:205], v149 offset:5120
	ds_read_b128 v[206:209], v149 offset:6144
	ds_read_b128 v[210:213], v149 offset:7168
	s_waitcnt vmcnt(8)
	s_waitcnt lgkmcnt(0)
	s_barrier
	s_waitcnt lgkmcnt(0)
	v_mfma_f32_16x16x32_bf16 v[124:127], v[150:153], v[182:185], v[124:127]
	v_mfma_f32_16x16x32_bf16 v[120:123], v[158:161], v[182:185], v[120:123]
	v_mfma_f32_16x16x32_bf16 v[108:111], v[150:153], v[190:193], v[108:111]
	v_mfma_f32_16x16x32_bf16 v[104:107], v[158:161], v[190:193], v[104:107]
	v_mfma_f32_16x16x32_bf16 v[92:95], v[150:153], v[198:201], v[92:95]
	v_mfma_f32_16x16x32_bf16 v[88:91], v[158:161], v[198:201], v[88:91]
	v_mfma_f32_16x16x32_bf16 v[76:79], v[150:153], v[206:209], v[76:79]
	v_mfma_f32_16x16x32_bf16 v[72:75], v[158:161], v[206:209], v[72:75]
	v_mfma_f32_16x16x32_bf16 v[124:127], v[154:157], v[186:189], v[124:127]
	v_mfma_f32_16x16x32_bf16 v[120:123], v[162:165], v[186:189], v[120:123]
	v_mfma_f32_16x16x32_bf16 v[108:111], v[154:157], v[194:197], v[108:111]
	v_mfma_f32_16x16x32_bf16 v[104:107], v[162:165], v[194:197], v[104:107]
	v_mfma_f32_16x16x32_bf16 v[92:95], v[154:157], v[202:205], v[92:95]
	v_mfma_f32_16x16x32_bf16 v[88:91], v[162:165], v[202:205], v[88:91]
	v_mfma_f32_16x16x32_bf16 v[76:79], v[154:157], v[210:213], v[76:79]
	v_mfma_f32_16x16x32_bf16 v[72:75], v[162:165], v[210:213], v[72:75]
	v_mfma_f32_16x16x32_bf16 v[116:119], v[166:169], v[182:185], v[116:119]
	v_mfma_f32_16x16x32_bf16 v[112:115], v[174:177], v[182:185], v[112:115]
	v_mfma_f32_16x16x32_bf16 v[100:103], v[166:169], v[190:193], v[100:103]
	v_mfma_f32_16x16x32_bf16 v[96:99], v[174:177], v[190:193], v[96:99]
	v_mfma_f32_16x16x32_bf16 v[84:87], v[166:169], v[198:201], v[84:87]
	v_mfma_f32_16x16x32_bf16 v[80:83], v[174:177], v[198:201], v[80:83]
	v_mfma_f32_16x16x32_bf16 v[68:71], v[166:169], v[206:209], v[68:71]
	v_mfma_f32_16x16x32_bf16 v[64:67], v[174:177], v[206:209], v[64:67]
	v_mfma_f32_16x16x32_bf16 v[116:119], v[170:173], v[186:189], v[116:119]
	v_mfma_f32_16x16x32_bf16 v[112:115], v[178:181], v[186:189], v[112:115]
	v_mfma_f32_16x16x32_bf16 v[100:103], v[170:173], v[194:197], v[100:103]
	v_mfma_f32_16x16x32_bf16 v[96:99], v[178:181], v[194:197], v[96:99]
	v_mfma_f32_16x16x32_bf16 v[84:87], v[170:173], v[202:205], v[84:87]
	v_mfma_f32_16x16x32_bf16 v[80:83], v[178:181], v[202:205], v[80:83]
	v_mfma_f32_16x16x32_bf16 v[68:71], v[170:173], v[210:213], v[68:71]
	v_mfma_f32_16x16x32_bf16 v[64:67], v[178:181], v[210:213], v[64:67]
	s_barrier
	s_add_i32 s36, s51, s11
	v_lshl_add_u64 v[214:215], s[40:41], 0, v[130:131]
	s_mov_b32 m0, s36
	v_lshl_add_u64 v[216:217], s[40:41], 0, v[134:135]
	global_load_lds_dwordx4 v[214:215], off
	s_add_i32 m0, s36, 0x2000
	s_add_u32 s36, s40, 0x80000
	s_addc_u32 s37, s41, 0
	s_add_i32 s60, s52, s11
	global_load_lds_dwordx4 v[216:217], off
	v_lshl_add_u64 v[182:183], s[36:37], 0, v[130:131]
	s_mov_b32 m0, s60
	v_lshl_add_u64 v[218:219], s[42:43], 0, v[128:129]
	global_load_lds_dwordx4 v[182:183], off
	v_lshl_add_u64 v[182:183], s[36:37], 0, v[134:135]
	s_add_i32 m0, s60, 0x2000
	v_lshl_add_u64 v[220:221], s[42:43], 0, v[132:133]
	global_load_lds_dwordx4 v[182:183], off
	s_mov_b32 m0, s35
	s_nop 0
	global_load_lds_dwordx4 v[218:219], off
	s_mov_b32 m0, s44
	s_nop 0
	global_load_lds_dwordx4 v[220:221], off
	ds_read_b128 v[182:185], v149 offset:16384
	ds_read_b128 v[186:189], v149 offset:17408
	ds_read_b128 v[190:193], v149 offset:18432
	ds_read_b128 v[194:197], v149 offset:19456
	ds_read_b128 v[198:201], v149 offset:20480
	ds_read_b128 v[202:205], v149 offset:21504
	ds_read_b128 v[206:209], v149 offset:22528
	ds_read_b128 v[210:213], v149 offset:23552
	s_waitcnt vmcnt(8)
	s_waitcnt lgkmcnt(0)
	s_barrier
	s_waitcnt lgkmcnt(0)
	v_mfma_f32_16x16x32_bf16 v[60:63], v[150:153], v[182:185], v[60:63]
	v_mfma_f32_16x16x32_bf16 v[56:59], v[158:161], v[182:185], v[56:59]
	v_mfma_f32_16x16x32_bf16 v[44:47], v[150:153], v[190:193], v[44:47]
	v_mfma_f32_16x16x32_bf16 v[40:43], v[158:161], v[190:193], v[40:43]
	v_mfma_f32_16x16x32_bf16 v[28:31], v[150:153], v[198:201], v[28:31]
	v_mfma_f32_16x16x32_bf16 v[24:27], v[158:161], v[198:201], v[24:27]
	v_mfma_f32_16x16x32_bf16 v[12:15], v[150:153], v[206:209], v[12:15]
	v_mfma_f32_16x16x32_bf16 v[8:11], v[158:161], v[206:209], v[8:11]
	v_mfma_f32_16x16x32_bf16 v[60:63], v[154:157], v[186:189], v[60:63]
	v_mfma_f32_16x16x32_bf16 v[56:59], v[162:165], v[186:189], v[56:59]
	v_mfma_f32_16x16x32_bf16 v[44:47], v[154:157], v[194:197], v[44:47]
	v_mfma_f32_16x16x32_bf16 v[40:43], v[162:165], v[194:197], v[40:43]
	v_mfma_f32_16x16x32_bf16 v[28:31], v[154:157], v[202:205], v[28:31]
	v_mfma_f32_16x16x32_bf16 v[24:27], v[162:165], v[202:205], v[24:27]
	v_mfma_f32_16x16x32_bf16 v[12:15], v[154:157], v[210:213], v[12:15]
	v_mfma_f32_16x16x32_bf16 v[8:11], v[162:165], v[210:213], v[8:11]
	v_mfma_f32_16x16x32_bf16 v[52:55], v[166:169], v[182:185], v[52:55]
	v_mfma_f32_16x16x32_bf16 v[48:51], v[174:177], v[182:185], v[48:51]
	v_mfma_f32_16x16x32_bf16 v[36:39], v[166:169], v[190:193], v[36:39]
	v_mfma_f32_16x16x32_bf16 v[32:35], v[174:177], v[190:193], v[32:35]
	v_mfma_f32_16x16x32_bf16 v[20:23], v[166:169], v[198:201], v[20:23]
	v_mfma_f32_16x16x32_bf16 v[16:19], v[174:177], v[198:201], v[16:19]
	v_mfma_f32_16x16x32_bf16 v[4:7], v[166:169], v[206:209], v[4:7]
	v_mfma_f32_16x16x32_bf16 v[0:3], v[174:177], v[206:209], v[0:3]
	v_mfma_f32_16x16x32_bf16 v[52:55], v[170:173], v[186:189], v[52:55]
	v_mfma_f32_16x16x32_bf16 v[48:51], v[178:181], v[186:189], v[48:51]
	v_mfma_f32_16x16x32_bf16 v[36:39], v[170:173], v[194:197], v[36:39]
	v_mfma_f32_16x16x32_bf16 v[32:35], v[178:181], v[194:197], v[32:35]
	v_mfma_f32_16x16x32_bf16 v[20:23], v[170:173], v[202:205], v[20:23]
	v_mfma_f32_16x16x32_bf16 v[16:19], v[178:181], v[202:205], v[16:19]
	v_mfma_f32_16x16x32_bf16 v[4:7], v[170:173], v[210:213], v[4:7]
	v_mfma_f32_16x16x32_bf16 v[0:3], v[178:181], v[210:213], v[0:3]
	s_barrier
	s_add_i32 s60, 0, 0x18000
	s_add_i32 s61, 0, 0x1c000
	v_add_u32_e32 v162, s60, v144
	v_add_u32_e32 v178, s61, v144
	ds_read_b128 v[150:153], v162
	ds_read_b128 v[154:157], v162 offset:1024
	ds_read_b128 v[158:161], v162 offset:2048
	ds_read_b128 v[162:165], v162 offset:3072
	ds_read_b128 v[166:169], v178
	ds_read_b128 v[170:173], v178 offset:1024
	ds_read_b128 v[174:177], v178 offset:2048
	ds_read_b128 v[178:181], v178 offset:3072
	s_add_u32 s36, s42, 0x80000
	s_addc_u32 s37, s43, 0
	s_mov_b32 m0, s45
	v_lshl_add_u64 v[182:183], s[36:37], 0, v[128:129]
	global_load_lds_dwordx4 v[182:183], off
	v_lshl_add_u64 v[182:183], s[36:37], 0, v[132:133]
	s_mov_b32 m0, s46
	s_nop 0
	global_load_lds_dwordx4 v[182:183], off
	ds_read_b128 v[182:185], v149 offset:32768
	ds_read_b128 v[186:189], v149 offset:33792
	ds_read_b128 v[190:193], v149 offset:34816
	ds_read_b128 v[194:197], v149 offset:35840
	ds_read_b128 v[198:201], v149 offset:36864
	ds_read_b128 v[202:205], v149 offset:37888
	ds_read_b128 v[206:209], v149 offset:38912
	ds_read_b128 v[210:213], v149 offset:39936
	s_waitcnt vmcnt(8)
	s_waitcnt lgkmcnt(0)
	s_barrier
	s_waitcnt lgkmcnt(0)
	v_mfma_f32_16x16x32_bf16 v[124:127], v[150:153], v[182:185], v[124:127]
	v_mfma_f32_16x16x32_bf16 v[120:123], v[158:161], v[182:185], v[120:123]
	v_mfma_f32_16x16x32_bf16 v[108:111], v[150:153], v[190:193], v[108:111]
	v_mfma_f32_16x16x32_bf16 v[104:107], v[158:161], v[190:193], v[104:107]
	v_mfma_f32_16x16x32_bf16 v[92:95], v[150:153], v[198:201], v[92:95]
	v_mfma_f32_16x16x32_bf16 v[88:91], v[158:161], v[198:201], v[88:91]
	v_mfma_f32_16x16x32_bf16 v[76:79], v[150:153], v[206:209], v[76:79]
	v_mfma_f32_16x16x32_bf16 v[72:75], v[158:161], v[206:209], v[72:75]
	v_mfma_f32_16x16x32_bf16 v[124:127], v[154:157], v[186:189], v[124:127]
	v_mfma_f32_16x16x32_bf16 v[120:123], v[162:165], v[186:189], v[120:123]
	v_mfma_f32_16x16x32_bf16 v[108:111], v[154:157], v[194:197], v[108:111]
	v_mfma_f32_16x16x32_bf16 v[104:107], v[162:165], v[194:197], v[104:107]
	v_mfma_f32_16x16x32_bf16 v[92:95], v[154:157], v[202:205], v[92:95]
	v_mfma_f32_16x16x32_bf16 v[88:91], v[162:165], v[202:205], v[88:91]
	v_mfma_f32_16x16x32_bf16 v[76:79], v[154:157], v[210:213], v[76:79]
	v_mfma_f32_16x16x32_bf16 v[72:75], v[162:165], v[210:213], v[72:75]
	v_mfma_f32_16x16x32_bf16 v[116:119], v[166:169], v[182:185], v[116:119]
	v_mfma_f32_16x16x32_bf16 v[112:115], v[174:177], v[182:185], v[112:115]
	v_mfma_f32_16x16x32_bf16 v[100:103], v[166:169], v[190:193], v[100:103]
	v_mfma_f32_16x16x32_bf16 v[96:99], v[174:177], v[190:193], v[96:99]
	v_mfma_f32_16x16x32_bf16 v[84:87], v[166:169], v[198:201], v[84:87]
	v_mfma_f32_16x16x32_bf16 v[80:83], v[174:177], v[198:201], v[80:83]
	v_mfma_f32_16x16x32_bf16 v[68:71], v[166:169], v[206:209], v[68:71]
	v_mfma_f32_16x16x32_bf16 v[64:67], v[174:177], v[206:209], v[64:67]
	v_mfma_f32_16x16x32_bf16 v[116:119], v[170:173], v[186:189], v[116:119]
	v_mfma_f32_16x16x32_bf16 v[112:115], v[178:181], v[186:189], v[112:115]
	v_mfma_f32_16x16x32_bf16 v[100:103], v[170:173], v[194:197], v[100:103]
	v_mfma_f32_16x16x32_bf16 v[96:99], v[178:181], v[194:197], v[96:99]
	v_mfma_f32_16x16x32_bf16 v[84:87], v[170:173], v[202:205], v[84:87]
	v_mfma_f32_16x16x32_bf16 v[80:83], v[178:181], v[202:205], v[80:83]
	v_mfma_f32_16x16x32_bf16 v[68:71], v[170:173], v[210:213], v[68:71]
	v_mfma_f32_16x16x32_bf16 v[64:67], v[178:181], v[210:213], v[64:67]
	s_barrier
	s_add_i32 s36, s60, s11
	v_lshl_add_u64 v[182:183], v[214:215], 0, s[14:15]
	s_mov_b32 m0, s36
	s_nop 0
	global_load_lds_dwordx4 v[182:183], off
	s_add_i32 m0, s36, 0x2000
	s_add_u32 s36, s40, 0x80080
	v_lshl_add_u64 v[182:183], v[216:217], 0, s[14:15]
	s_addc_u32 s37, s41, 0
	s_add_i32 s40, s61, s11
	global_load_lds_dwordx4 v[182:183], off
	v_lshl_add_u64 v[182:183], s[36:37], 0, v[130:131]
	s_mov_b32 m0, s40
	s_nop 0
	global_load_lds_dwordx4 v[182:183], off
	v_lshl_add_u64 v[182:183], s[36:37], 0, v[134:135]
	s_add_i32 m0, s40, 0x2000
	s_nop 0
	global_load_lds_dwordx4 v[182:183], off
	v_lshl_add_u64 v[182:183], v[218:219], 0, s[14:15]
	s_mov_b32 m0, s49
	s_nop 0
	global_load_lds_dwordx4 v[182:183], off
	v_lshl_add_u64 v[182:183], v[220:221], 0, s[14:15]
	s_mov_b32 m0, s50
	s_nop 0
	global_load_lds_dwordx4 v[182:183], off
	ds_read_b128 v[182:185], v149 offset:49152
	ds_read_b128 v[186:189], v149 offset:50176
	ds_read_b128 v[190:193], v149 offset:51200
	ds_read_b128 v[194:197], v149 offset:52224
	ds_read_b128 v[198:201], v149 offset:53248
	ds_read_b128 v[202:205], v149 offset:54272
	ds_read_b128 v[206:209], v149 offset:55296
	ds_read_b128 v[210:213], v149 offset:56320
	s_waitcnt vmcnt(8)
	s_waitcnt lgkmcnt(0)
	s_barrier
	s_waitcnt lgkmcnt(0)
	v_mfma_f32_16x16x32_bf16 v[60:63], v[150:153], v[182:185], v[60:63]
	v_mfma_f32_16x16x32_bf16 v[56:59], v[158:161], v[182:185], v[56:59]
	v_mfma_f32_16x16x32_bf16 v[44:47], v[150:153], v[190:193], v[44:47]
	v_mfma_f32_16x16x32_bf16 v[40:43], v[158:161], v[190:193], v[40:43]
	v_mfma_f32_16x16x32_bf16 v[28:31], v[150:153], v[198:201], v[28:31]
	v_mfma_f32_16x16x32_bf16 v[24:27], v[158:161], v[198:201], v[24:27]
	v_mfma_f32_16x16x32_bf16 v[12:15], v[150:153], v[206:209], v[12:15]
	v_mfma_f32_16x16x32_bf16 v[8:11], v[158:161], v[206:209], v[8:11]
	v_mfma_f32_16x16x32_bf16 v[60:63], v[154:157], v[186:189], v[60:63]
	v_mfma_f32_16x16x32_bf16 v[56:59], v[162:165], v[186:189], v[56:59]
	v_mfma_f32_16x16x32_bf16 v[44:47], v[154:157], v[194:197], v[44:47]
	v_mfma_f32_16x16x32_bf16 v[40:43], v[162:165], v[194:197], v[40:43]
	v_mfma_f32_16x16x32_bf16 v[28:31], v[154:157], v[202:205], v[28:31]
	v_mfma_f32_16x16x32_bf16 v[24:27], v[162:165], v[202:205], v[24:27]
	v_mfma_f32_16x16x32_bf16 v[12:15], v[154:157], v[210:213], v[12:15]
	v_mfma_f32_16x16x32_bf16 v[8:11], v[162:165], v[210:213], v[8:11]
	v_mfma_f32_16x16x32_bf16 v[52:55], v[166:169], v[182:185], v[52:55]
	v_mfma_f32_16x16x32_bf16 v[48:51], v[174:177], v[182:185], v[48:51]
	v_mfma_f32_16x16x32_bf16 v[36:39], v[166:169], v[190:193], v[36:39]
	v_mfma_f32_16x16x32_bf16 v[32:35], v[174:177], v[190:193], v[32:35]
	v_mfma_f32_16x16x32_bf16 v[20:23], v[166:169], v[198:201], v[20:23]
	v_mfma_f32_16x16x32_bf16 v[16:19], v[174:177], v[198:201], v[16:19]
	v_mfma_f32_16x16x32_bf16 v[4:7], v[166:169], v[206:209], v[4:7]
	v_mfma_f32_16x16x32_bf16 v[0:3], v[174:177], v[206:209], v[0:3]
	v_mfma_f32_16x16x32_bf16 v[52:55], v[170:173], v[186:189], v[52:55]
	v_mfma_f32_16x16x32_bf16 v[48:51], v[178:181], v[186:189], v[48:51]
	v_mfma_f32_16x16x32_bf16 v[36:39], v[170:173], v[194:197], v[36:39]
	v_mfma_f32_16x16x32_bf16 v[32:35], v[178:181], v[194:197], v[32:35]
	v_mfma_f32_16x16x32_bf16 v[20:23], v[170:173], v[202:205], v[20:23]
	v_mfma_f32_16x16x32_bf16 v[16:19], v[178:181], v[202:205], v[16:19]
	v_mfma_f32_16x16x32_bf16 v[4:7], v[170:173], v[210:213], v[4:7]
	v_mfma_f32_16x16x32_bf16 v[0:3], v[178:181], v[210:213], v[0:3]
	s_barrier
	s_add_i32 s59, s59, 2
	s_add_u32 s57, s57, 0x100
	s_addc_u32 s58, s58, 0
	s_cmp_gt_u32 s59, 29
	s_mov_b64 s[36:37], s[38:39]
	s_cbranch_scc0 .LBB0_159
	s_and_b64 vcc, exec, s[6:7]
	s_cbranch_vccz .LBB0_162
	s_barrier

.LBB0_248:
	ds_read_b128 v[144:147], v161
	ds_read_b128 v[148:151], v161 offset:1024
	ds_read_b128 v[152:155], v161 offset:2048
	ds_read_b128 v[164:167], v161 offset:3072
	ds_read_b128 v[168:171], v162
	ds_read_b128 v[172:175], v162 offset:1024
	ds_read_b128 v[176:179], v162 offset:2048
	ds_read_b128 v[180:183], v162 offset:3072
	s_add_u32 s6, s8, 0x100
	s_addc_u32 s7, s9, 0
	s_cmpk_eq_i32 s65, 0x54
	s_cselect_b32 s49, s43, s7
	s_cselect_b32 s48, s42, s6
	s_cselect_b32 s47, s45, s64
	s_cselect_b32 s46, s44, s63
	v_lshl_add_u64 v[184:185], s[8:9], 0, v[136:137]
	s_add_i32 m0, s53, 0xc000
	s_nop 0
	global_load_lds_dwordx4 v[184:185], off
	v_lshl_add_u64 v[184:185], s[8:9], 0, v[138:139]
	s_add_i32 m0, s53, 0xe000
	s_nop 0
	global_load_lds_dwordx4 v[184:185], off
	ds_read_b128 v[184:187], v163
	ds_read_b128 v[188:191], v163 offset:1024
	ds_read_b128 v[192:195], v163 offset:2048
	ds_read_b128 v[196:199], v163 offset:3072
	ds_read_b128 v[200:203], v163 offset:4096
	ds_read_b128 v[204:207], v163 offset:5120
	ds_read_b128 v[208:211], v163 offset:6144
	ds_read_b128 v[212:215], v163 offset:7168
	s_waitcnt vmcnt(8)
	s_waitcnt lgkmcnt(0)
	s_barrier
	s_waitcnt lgkmcnt(0)
	v_mfma_f32_16x16x32_bf16 v[124:127], v[144:147], v[184:187], v[124:127]
	v_mfma_f32_16x16x32_bf16 v[120:123], v[152:155], v[184:187], v[120:123]
	v_mfma_f32_16x16x32_bf16 v[108:111], v[144:147], v[192:195], v[108:111]
	v_mfma_f32_16x16x32_bf16 v[104:107], v[152:155], v[192:195], v[104:107]
	v_mfma_f32_16x16x32_bf16 v[92:95], v[144:147], v[200:203], v[92:95]
	v_mfma_f32_16x16x32_bf16 v[88:91], v[152:155], v[200:203], v[88:91]
	v_mfma_f32_16x16x32_bf16 v[76:79], v[144:147], v[208:211], v[76:79]
	v_mfma_f32_16x16x32_bf16 v[72:75], v[152:155], v[208:211], v[72:75]
	v_mfma_f32_16x16x32_bf16 v[124:127], v[148:151], v[188:191], v[124:127]
	v_mfma_f32_16x16x32_bf16 v[120:123], v[164:167], v[188:191], v[120:123]
	v_mfma_f32_16x16x32_bf16 v[108:111], v[148:151], v[196:199], v[108:111]
	v_mfma_f32_16x16x32_bf16 v[104:107], v[164:167], v[196:199], v[104:107]
	v_mfma_f32_16x16x32_bf16 v[92:95], v[148:151], v[204:207], v[92:95]
	v_mfma_f32_16x16x32_bf16 v[88:91], v[164:167], v[204:207], v[88:91]
	v_mfma_f32_16x16x32_bf16 v[76:79], v[148:151], v[212:215], v[76:79]
	v_mfma_f32_16x16x32_bf16 v[72:75], v[164:167], v[212:215], v[72:75]
	v_mfma_f32_16x16x32_bf16 v[116:119], v[168:171], v[184:187], v[116:119]
	v_mfma_f32_16x16x32_bf16 v[112:115], v[176:179], v[184:187], v[112:115]
	v_mfma_f32_16x16x32_bf16 v[100:103], v[168:171], v[192:195], v[100:103]
	v_mfma_f32_16x16x32_bf16 v[96:99], v[176:179], v[192:195], v[96:99]
	v_mfma_f32_16x16x32_bf16 v[84:87], v[168:171], v[200:203], v[84:87]
	v_mfma_f32_16x16x32_bf16 v[80:83], v[176:179], v[200:203], v[80:83]
	v_mfma_f32_16x16x32_bf16 v[68:71], v[168:171], v[208:211], v[68:71]
	v_mfma_f32_16x16x32_bf16 v[64:67], v[176:179], v[208:211], v[64:67]
	v_mfma_f32_16x16x32_bf16 v[116:119], v[172:175], v[188:191], v[116:119]
	v_mfma_f32_16x16x32_bf16 v[112:115], v[180:183], v[188:191], v[112:115]
	v_mfma_f32_16x16x32_bf16 v[100:103], v[172:175], v[196:199], v[100:103]
	v_mfma_f32_16x16x32_bf16 v[96:99], v[180:183], v[196:199], v[96:99]
	v_mfma_f32_16x16x32_bf16 v[84:87], v[172:175], v[204:207], v[84:87]
	v_mfma_f32_16x16x32_bf16 v[80:83], v[180:183], v[204:207], v[80:83]
	v_mfma_f32_16x16x32_bf16 v[68:71], v[172:175], v[212:215], v[68:71]
	v_mfma_f32_16x16x32_bf16 v[64:67], v[180:183], v[212:215], v[64:67]
	s_barrier
	s_add_i32 s8, s58, s21
	v_lshl_add_u64 v[216:217], s[46:47], 0, v[130:131]
	s_mov_b32 m0, s8
	v_lshl_add_u64 v[218:219], s[46:47], 0, v[134:135]
	global_load_lds_dwordx4 v[216:217], off
	s_add_i32 m0, s8, 0x2000
	s_add_u32 s8, s46, 0x160000
	s_addc_u32 s9, s47, 0
	s_add_i32 s66, s59, s21
	global_load_lds_dwordx4 v[218:219], off
	v_lshl_add_u64 v[184:185], s[8:9], 0, v[130:131]
	s_mov_b32 m0, s66
	v_lshl_add_u64 v[220:221], s[48:49], 0, v[128:129]
	global_load_lds_dwordx4 v[184:185], off
	v_lshl_add_u64 v[184:185], s[8:9], 0, v[134:135]
	s_add_i32 m0, s66, 0x2000
	v_lshl_add_u64 v[222:223], s[48:49], 0, v[132:133]
	global_load_lds_dwordx4 v[184:185], off
	s_mov_b32 m0, s53
	s_nop 0
	global_load_lds_dwordx4 v[220:221], off
	s_mov_b32 m0, s54
	s_nop 0
	global_load_lds_dwordx4 v[222:223], off
	ds_read_b128 v[184:187], v163 offset:16384
	ds_read_b128 v[188:191], v163 offset:17408
	ds_read_b128 v[192:195], v163 offset:18432
	ds_read_b128 v[196:199], v163 offset:19456
	ds_read_b128 v[200:203], v163 offset:20480
	ds_read_b128 v[204:207], v163 offset:21504
	ds_read_b128 v[208:211], v163 offset:22528
	ds_read_b128 v[212:215], v163 offset:23552
	s_waitcnt vmcnt(8)
	s_waitcnt lgkmcnt(0)
	s_barrier
	s_waitcnt lgkmcnt(0)
	v_mfma_f32_16x16x32_bf16 v[60:63], v[144:147], v[184:187], v[60:63]
	v_mfma_f32_16x16x32_bf16 v[56:59], v[152:155], v[184:187], v[56:59]
	v_mfma_f32_16x16x32_bf16 v[44:47], v[144:147], v[192:195], v[44:47]
	v_mfma_f32_16x16x32_bf16 v[40:43], v[152:155], v[192:195], v[40:43]
	v_mfma_f32_16x16x32_bf16 v[28:31], v[144:147], v[200:203], v[28:31]
	v_mfma_f32_16x16x32_bf16 v[24:27], v[152:155], v[200:203], v[24:27]
	v_mfma_f32_16x16x32_bf16 v[12:15], v[144:147], v[208:211], v[12:15]
	v_mfma_f32_16x16x32_bf16 v[8:11], v[152:155], v[208:211], v[8:11]
	v_mfma_f32_16x16x32_bf16 v[60:63], v[148:151], v[188:191], v[60:63]
	v_mfma_f32_16x16x32_bf16 v[56:59], v[164:167], v[188:191], v[56:59]
	v_mfma_f32_16x16x32_bf16 v[44:47], v[148:151], v[196:199], v[44:47]
	v_mfma_f32_16x16x32_bf16 v[40:43], v[164:167], v[196:199], v[40:43]
	v_mfma_f32_16x16x32_bf16 v[28:31], v[148:151], v[204:207], v[28:31]
	v_mfma_f32_16x16x32_bf16 v[24:27], v[164:167], v[204:207], v[24:27]
	v_mfma_f32_16x16x32_bf16 v[12:15], v[148:151], v[212:215], v[12:15]
	v_mfma_f32_16x16x32_bf16 v[8:11], v[164:167], v[212:215], v[8:11]
	v_mfma_f32_16x16x32_bf16 v[52:55], v[168:171], v[184:187], v[52:55]
	v_mfma_f32_16x16x32_bf16 v[48:51], v[176:179], v[184:187], v[48:51]
	v_mfma_f32_16x16x32_bf16 v[36:39], v[168:171], v[192:195], v[36:39]
	v_mfma_f32_16x16x32_bf16 v[32:35], v[176:179], v[192:195], v[32:35]
	v_mfma_f32_16x16x32_bf16 v[20:23], v[168:171], v[200:203], v[20:23]
	v_mfma_f32_16x16x32_bf16 v[16:19], v[176:179], v[200:203], v[16:19]
	v_mfma_f32_16x16x32_bf16 v[4:7], v[168:171], v[208:211], v[4:7]
	v_mfma_f32_16x16x32_bf16 v[0:3], v[176:179], v[208:211], v[0:3]
	v_mfma_f32_16x16x32_bf16 v[52:55], v[172:175], v[188:191], v[52:55]
	v_mfma_f32_16x16x32_bf16 v[48:51], v[180:183], v[188:191], v[48:51]
	v_mfma_f32_16x16x32_bf16 v[36:39], v[172:175], v[196:199], v[36:39]
	v_mfma_f32_16x16x32_bf16 v[32:35], v[180:183], v[196:199], v[32:35]
	v_mfma_f32_16x16x32_bf16 v[20:23], v[172:175], v[204:207], v[20:23]
	v_mfma_f32_16x16x32_bf16 v[16:19], v[180:183], v[204:207], v[16:19]
	v_mfma_f32_16x16x32_bf16 v[4:7], v[172:175], v[212:215], v[4:7]
	v_mfma_f32_16x16x32_bf16 v[0:3], v[180:183], v[212:215], v[0:3]
	s_barrier
	s_add_i32 s66, 0, 0x18000
	s_add_i32 s67, 0, 0x1c000
	v_add_u32_e32 v164, s66, v156
	v_add_u32_e32 v180, s67, v156
	ds_read_b128 v[144:147], v164
	ds_read_b128 v[148:151], v164 offset:1024
	ds_read_b128 v[152:155], v164 offset:2048
	ds_read_b128 v[164:167], v164 offset:3072
	ds_read_b128 v[168:171], v180
	ds_read_b128 v[172:175], v180 offset:1024
	ds_read_b128 v[176:179], v180 offset:2048
	ds_read_b128 v[180:183], v180 offset:3072
	s_add_u32 s8, s48, 0x160000
	s_addc_u32 s9, s49, 0
	s_mov_b32 m0, s55
	v_lshl_add_u64 v[184:185], s[8:9], 0, v[128:129]
	global_load_lds_dwordx4 v[184:185], off
	v_lshl_add_u64 v[184:185], s[8:9], 0, v[132:133]
	s_mov_b32 m0, s56
	s_nop 0
	global_load_lds_dwordx4 v[184:185], off
	ds_read_b128 v[184:187], v163 offset:32768
	ds_read_b128 v[188:191], v163 offset:33792
	ds_read_b128 v[192:195], v163 offset:34816
	ds_read_b128 v[196:199], v163 offset:35840
	ds_read_b128 v[200:203], v163 offset:36864
	ds_read_b128 v[204:207], v163 offset:37888
	ds_read_b128 v[208:211], v163 offset:38912
	ds_read_b128 v[212:215], v163 offset:39936
	s_waitcnt vmcnt(8)
	s_waitcnt lgkmcnt(0)
	s_barrier
	s_waitcnt lgkmcnt(0)
	v_mfma_f32_16x16x32_bf16 v[124:127], v[144:147], v[184:187], v[124:127]
	v_mfma_f32_16x16x32_bf16 v[120:123], v[152:155], v[184:187], v[120:123]
	v_mfma_f32_16x16x32_bf16 v[108:111], v[144:147], v[192:195], v[108:111]
	v_mfma_f32_16x16x32_bf16 v[104:107], v[152:155], v[192:195], v[104:107]
	v_mfma_f32_16x16x32_bf16 v[92:95], v[144:147], v[200:203], v[92:95]
	v_mfma_f32_16x16x32_bf16 v[88:91], v[152:155], v[200:203], v[88:91]
	v_mfma_f32_16x16x32_bf16 v[76:79], v[144:147], v[208:211], v[76:79]
	v_mfma_f32_16x16x32_bf16 v[72:75], v[152:155], v[208:211], v[72:75]
	v_mfma_f32_16x16x32_bf16 v[124:127], v[148:151], v[188:191], v[124:127]
	v_mfma_f32_16x16x32_bf16 v[120:123], v[164:167], v[188:191], v[120:123]
	v_mfma_f32_16x16x32_bf16 v[108:111], v[148:151], v[196:199], v[108:111]
	v_mfma_f32_16x16x32_bf16 v[104:107], v[164:167], v[196:199], v[104:107]
	v_mfma_f32_16x16x32_bf16 v[92:95], v[148:151], v[204:207], v[92:95]
	v_mfma_f32_16x16x32_bf16 v[88:91], v[164:167], v[204:207], v[88:91]
	v_mfma_f32_16x16x32_bf16 v[76:79], v[148:151], v[212:215], v[76:79]
	v_mfma_f32_16x16x32_bf16 v[72:75], v[164:167], v[212:215], v[72:75]
	v_mfma_f32_16x16x32_bf16 v[116:119], v[168:171], v[184:187], v[116:119]
	v_mfma_f32_16x16x32_bf16 v[112:115], v[176:179], v[184:187], v[112:115]
	v_mfma_f32_16x16x32_bf16 v[100:103], v[168:171], v[192:195], v[100:103]
	v_mfma_f32_16x16x32_bf16 v[96:99], v[176:179], v[192:195], v[96:99]
	v_mfma_f32_16x16x32_bf16 v[84:87], v[168:171], v[200:203], v[84:87]
	v_mfma_f32_16x16x32_bf16 v[80:83], v[176:179], v[200:203], v[80:83]
	v_mfma_f32_16x16x32_bf16 v[68:71], v[168:171], v[208:211], v[68:71]
	v_mfma_f32_16x16x32_bf16 v[64:67], v[176:179], v[208:211], v[64:67]
	v_mfma_f32_16x16x32_bf16 v[116:119], v[172:175], v[188:191], v[116:119]
	v_mfma_f32_16x16x32_bf16 v[112:115], v[180:183], v[188:191], v[112:115]
	v_mfma_f32_16x16x32_bf16 v[100:103], v[172:175], v[196:199], v[100:103]
	v_mfma_f32_16x16x32_bf16 v[96:99], v[180:183], v[196:199], v[96:99]
	v_mfma_f32_16x16x32_bf16 v[84:87], v[172:175], v[204:207], v[84:87]
	v_mfma_f32_16x16x32_bf16 v[80:83], v[180:183], v[204:207], v[80:83]
	v_mfma_f32_16x16x32_bf16 v[68:71], v[172:175], v[212:215], v[68:71]
	v_mfma_f32_16x16x32_bf16 v[64:67], v[180:183], v[212:215], v[64:67]
	s_barrier
	s_add_i32 s8, s66, s21
	v_lshl_add_u64 v[184:185], v[216:217], 0, s[36:37]
	s_mov_b32 m0, s8
	s_nop 0
	global_load_lds_dwordx4 v[184:185], off
	s_add_i32 m0, s8, 0x2000
	s_add_u32 s8, s46, 0x160080
	v_lshl_add_u64 v[184:185], v[218:219], 0, s[36:37]
	s_addc_u32 s9, s47, 0
	s_add_i32 s46, s67, s21
	global_load_lds_dwordx4 v[184:185], off
	v_lshl_add_u64 v[184:185], s[8:9], 0, v[130:131]
	s_mov_b32 m0, s46
	s_nop 0
	global_load_lds_dwordx4 v[184:185], off
	v_lshl_add_u64 v[184:185], s[8:9], 0, v[134:135]
	s_add_i32 m0, s46, 0x2000
	s_nop 0
	global_load_lds_dwordx4 v[184:185], off
	v_lshl_add_u64 v[184:185], v[220:221], 0, s[36:37]
	s_mov_b32 m0, s26
	s_nop 0
	global_load_lds_dwordx4 v[184:185], off
	v_lshl_add_u64 v[184:185], v[222:223], 0, s[36:37]
	s_mov_b32 m0, s27
	s_nop 0
	global_load_lds_dwordx4 v[184:185], off
	ds_read_b128 v[184:187], v163 offset:49152
	ds_read_b128 v[188:191], v163 offset:50176
	ds_read_b128 v[192:195], v163 offset:51200
	ds_read_b128 v[196:199], v163 offset:52224
	ds_read_b128 v[200:203], v163 offset:53248
	ds_read_b128 v[204:207], v163 offset:54272
	ds_read_b128 v[208:211], v163 offset:55296
	ds_read_b128 v[212:215], v163 offset:56320
	s_waitcnt vmcnt(8)
	s_waitcnt lgkmcnt(0)
	s_barrier
	s_waitcnt lgkmcnt(0)
	v_mfma_f32_16x16x32_bf16 v[60:63], v[144:147], v[184:187], v[60:63]
	v_mfma_f32_16x16x32_bf16 v[56:59], v[152:155], v[184:187], v[56:59]
	v_mfma_f32_16x16x32_bf16 v[44:47], v[144:147], v[192:195], v[44:47]
	v_mfma_f32_16x16x32_bf16 v[40:43], v[152:155], v[192:195], v[40:43]
	v_mfma_f32_16x16x32_bf16 v[28:31], v[144:147], v[200:203], v[28:31]
	v_mfma_f32_16x16x32_bf16 v[24:27], v[152:155], v[200:203], v[24:27]
	v_mfma_f32_16x16x32_bf16 v[12:15], v[144:147], v[208:211], v[12:15]
	v_mfma_f32_16x16x32_bf16 v[8:11], v[152:155], v[208:211], v[8:11]
	v_mfma_f32_16x16x32_bf16 v[60:63], v[148:151], v[188:191], v[60:63]
	v_mfma_f32_16x16x32_bf16 v[56:59], v[164:167], v[188:191], v[56:59]
	v_mfma_f32_16x16x32_bf16 v[44:47], v[148:151], v[196:199], v[44:47]
	v_mfma_f32_16x16x32_bf16 v[40:43], v[164:167], v[196:199], v[40:43]
	v_mfma_f32_16x16x32_bf16 v[28:31], v[148:151], v[204:207], v[28:31]
	v_mfma_f32_16x16x32_bf16 v[24:27], v[164:167], v[204:207], v[24:27]
	v_mfma_f32_16x16x32_bf16 v[12:15], v[148:151], v[212:215], v[12:15]
	v_mfma_f32_16x16x32_bf16 v[8:11], v[164:167], v[212:215], v[8:11]
	v_mfma_f32_16x16x32_bf16 v[52:55], v[168:171], v[184:187], v[52:55]
	v_mfma_f32_16x16x32_bf16 v[48:51], v[176:179], v[184:187], v[48:51]
	v_mfma_f32_16x16x32_bf16 v[36:39], v[168:171], v[192:195], v[36:39]
	v_mfma_f32_16x16x32_bf16 v[32:35], v[176:179], v[192:195], v[32:35]
	v_mfma_f32_16x16x32_bf16 v[20:23], v[168:171], v[200:203], v[20:23]
	v_mfma_f32_16x16x32_bf16 v[16:19], v[176:179], v[200:203], v[16:19]
	v_mfma_f32_16x16x32_bf16 v[4:7], v[168:171], v[208:211], v[4:7]
	v_mfma_f32_16x16x32_bf16 v[0:3], v[176:179], v[208:211], v[0:3]
	v_mfma_f32_16x16x32_bf16 v[52:55], v[172:175], v[188:191], v[52:55]
	v_mfma_f32_16x16x32_bf16 v[48:51], v[180:183], v[188:191], v[48:51]
	v_mfma_f32_16x16x32_bf16 v[36:39], v[172:175], v[196:199], v[36:39]
	v_mfma_f32_16x16x32_bf16 v[32:35], v[180:183], v[196:199], v[32:35]
	v_mfma_f32_16x16x32_bf16 v[20:23], v[172:175], v[204:207], v[20:23]
	v_mfma_f32_16x16x32_bf16 v[16:19], v[180:183], v[204:207], v[16:19]
	v_mfma_f32_16x16x32_bf16 v[4:7], v[172:175], v[212:215], v[4:7]
	v_mfma_f32_16x16x32_bf16 v[0:3], v[180:183], v[212:215], v[0:3]
	s_barrier
	s_add_i32 s65, s65, 2
	s_add_u32 s63, s63, 0x100
	s_addc_u32 s64, s64, 0
	s_cmpk_gt_u32 s65, 0x55
	s_mov_b64 s[8:9], s[6:7]
	s_cbranch_scc0 .LBB0_248
	s_and_b64 vcc, exec, s[28:29]
	s_cbranch_vccz .LBB0_251
	s_barrier

.LBB0_387:
	ds_read_b128 v[146:149], v156
	ds_read_b128 v[160:163], v156 offset:1024
	ds_read_b128 v[164:167], v156 offset:2048
	ds_read_b128 v[168:171], v156 offset:3072
	ds_read_b128 v[172:175], v157
	ds_read_b128 v[176:179], v157 offset:1024
	ds_read_b128 v[180:183], v157 offset:2048
	ds_read_b128 v[184:187], v157 offset:3072
	s_add_u32 s38, s36, 0x100
	s_addc_u32 s39, s37, 0
	s_cmp_eq_u32 s64, 28
	s_cselect_b32 s43, s29, s39
	s_cselect_b32 s42, s60, s38
	s_cselect_b32 s41, s19, s63
	s_cselect_b32 s40, s61, s62
	v_lshl_add_u64 v[150:151], s[36:37], 0, v[138:139]
	s_add_i32 m0, s46, 0xc000
	s_nop 0
	global_load_lds_dwordx4 v[150:151], off
	v_lshl_add_u64 v[150:151], s[36:37], 0, v[140:141]
	s_add_i32 m0, s46, 0xe000
	s_nop 0
	global_load_lds_dwordx4 v[150:151], off
	ds_read_b128 v[188:191], v158
	ds_read_b128 v[192:195], v158 offset:1024
	ds_read_b128 v[196:199], v158 offset:2048
	ds_read_b128 v[200:203], v158 offset:3072
	ds_read_b128 v[204:207], v158 offset:4096
	ds_read_b128 v[208:211], v158 offset:5120
	ds_read_b128 v[212:215], v158 offset:6144
	ds_read_b128 v[216:219], v158 offset:7168
	s_waitcnt vmcnt(8)
	s_waitcnt lgkmcnt(0)
	s_barrier
	s_waitcnt lgkmcnt(0)
	v_mfma_f32_16x16x32_bf16 v[124:127], v[146:149], v[188:191], v[124:127]
	v_mfma_f32_16x16x32_bf16 v[120:123], v[164:167], v[188:191], v[120:123]
	v_mfma_f32_16x16x32_bf16 v[108:111], v[146:149], v[196:199], v[108:111]
	v_mfma_f32_16x16x32_bf16 v[104:107], v[164:167], v[196:199], v[104:107]
	v_mfma_f32_16x16x32_bf16 v[92:95], v[146:149], v[204:207], v[92:95]
	v_mfma_f32_16x16x32_bf16 v[88:91], v[164:167], v[204:207], v[88:91]
	v_mfma_f32_16x16x32_bf16 v[76:79], v[146:149], v[212:215], v[76:79]
	v_mfma_f32_16x16x32_bf16 v[72:75], v[164:167], v[212:215], v[72:75]
	v_mfma_f32_16x16x32_bf16 v[124:127], v[160:163], v[192:195], v[124:127]
	v_mfma_f32_16x16x32_bf16 v[120:123], v[168:171], v[192:195], v[120:123]
	v_mfma_f32_16x16x32_bf16 v[108:111], v[160:163], v[200:203], v[108:111]
	v_mfma_f32_16x16x32_bf16 v[104:107], v[168:171], v[200:203], v[104:107]
	v_mfma_f32_16x16x32_bf16 v[92:95], v[160:163], v[208:211], v[92:95]
	v_mfma_f32_16x16x32_bf16 v[88:91], v[168:171], v[208:211], v[88:91]
	v_mfma_f32_16x16x32_bf16 v[76:79], v[160:163], v[216:219], v[76:79]
	v_mfma_f32_16x16x32_bf16 v[72:75], v[168:171], v[216:219], v[72:75]
	v_mfma_f32_16x16x32_bf16 v[116:119], v[172:175], v[188:191], v[116:119]
	v_mfma_f32_16x16x32_bf16 v[112:115], v[180:183], v[188:191], v[112:115]
	v_mfma_f32_16x16x32_bf16 v[100:103], v[172:175], v[196:199], v[100:103]
	v_mfma_f32_16x16x32_bf16 v[96:99], v[180:183], v[196:199], v[96:99]
	v_mfma_f32_16x16x32_bf16 v[84:87], v[172:175], v[204:207], v[84:87]
	v_mfma_f32_16x16x32_bf16 v[80:83], v[180:183], v[204:207], v[80:83]
	v_mfma_f32_16x16x32_bf16 v[68:71], v[172:175], v[212:215], v[68:71]
	v_mfma_f32_16x16x32_bf16 v[64:67], v[180:183], v[212:215], v[64:67]
	v_mfma_f32_16x16x32_bf16 v[116:119], v[176:179], v[192:195], v[116:119]
	v_mfma_f32_16x16x32_bf16 v[112:115], v[184:187], v[192:195], v[112:115]
	v_mfma_f32_16x16x32_bf16 v[100:103], v[176:179], v[200:203], v[100:103]
	v_mfma_f32_16x16x32_bf16 v[96:99], v[184:187], v[200:203], v[96:99]
	v_mfma_f32_16x16x32_bf16 v[84:87], v[176:179], v[208:211], v[84:87]
	v_mfma_f32_16x16x32_bf16 v[80:83], v[184:187], v[208:211], v[80:83]
	v_mfma_f32_16x16x32_bf16 v[68:71], v[176:179], v[216:219], v[68:71]
	v_mfma_f32_16x16x32_bf16 v[64:67], v[184:187], v[216:219], v[64:67]
	s_barrier
	s_add_i32 s36, s55, s11
	v_lshl_add_u64 v[150:151], s[40:41], 0, v[130:131]
	s_mov_b32 m0, s36
	v_lshl_add_u64 v[220:221], s[40:41], 0, v[134:135]
	global_load_lds_dwordx4 v[150:151], off
	s_add_i32 m0, s36, 0x2000
	s_add_u32 s36, s40, 0x80000
	s_addc_u32 s37, s41, 0
	s_add_i32 s65, s56, s11
	global_load_lds_dwordx4 v[220:221], off
	v_lshl_add_u64 v[188:189], s[36:37], 0, v[130:131]
	s_mov_b32 m0, s65
	v_lshl_add_u64 v[222:223], s[42:43], 0, v[128:129]
	global_load_lds_dwordx4 v[188:189], off
	v_lshl_add_u64 v[188:189], s[36:37], 0, v[134:135]
	s_add_i32 m0, s65, 0x2000
	v_lshl_add_u64 v[224:225], s[42:43], 0, v[132:133]
	global_load_lds_dwordx4 v[188:189], off
	s_mov_b32 m0, s46
	s_nop 0
	global_load_lds_dwordx4 v[222:223], off
	s_mov_b32 m0, s47
	s_nop 0
	global_load_lds_dwordx4 v[224:225], off
	ds_read_b128 v[188:191], v158 offset:16384
	ds_read_b128 v[192:195], v158 offset:17408
	ds_read_b128 v[196:199], v158 offset:18432
	ds_read_b128 v[200:203], v158 offset:19456
	ds_read_b128 v[204:207], v158 offset:20480
	ds_read_b128 v[208:211], v158 offset:21504
	ds_read_b128 v[212:215], v158 offset:22528
	ds_read_b128 v[216:219], v158 offset:23552
	s_waitcnt vmcnt(8)
	s_waitcnt lgkmcnt(0)
	s_barrier
	s_waitcnt lgkmcnt(0)
	v_mfma_f32_16x16x32_bf16 v[60:63], v[146:149], v[188:191], v[60:63]
	v_mfma_f32_16x16x32_bf16 v[56:59], v[164:167], v[188:191], v[56:59]
	v_mfma_f32_16x16x32_bf16 v[44:47], v[146:149], v[196:199], v[44:47]
	v_mfma_f32_16x16x32_bf16 v[40:43], v[164:167], v[196:199], v[40:43]
	v_mfma_f32_16x16x32_bf16 v[28:31], v[146:149], v[204:207], v[28:31]
	v_mfma_f32_16x16x32_bf16 v[24:27], v[164:167], v[204:207], v[24:27]
	v_mfma_f32_16x16x32_bf16 v[12:15], v[146:149], v[212:215], v[12:15]
	v_mfma_f32_16x16x32_bf16 v[8:11], v[164:167], v[212:215], v[8:11]
	v_mfma_f32_16x16x32_bf16 v[60:63], v[160:163], v[192:195], v[60:63]
	v_mfma_f32_16x16x32_bf16 v[56:59], v[168:171], v[192:195], v[56:59]
	v_mfma_f32_16x16x32_bf16 v[44:47], v[160:163], v[200:203], v[44:47]
	v_mfma_f32_16x16x32_bf16 v[40:43], v[168:171], v[200:203], v[40:43]
	v_mfma_f32_16x16x32_bf16 v[28:31], v[160:163], v[208:211], v[28:31]
	v_mfma_f32_16x16x32_bf16 v[24:27], v[168:171], v[208:211], v[24:27]
	v_mfma_f32_16x16x32_bf16 v[12:15], v[160:163], v[216:219], v[12:15]
	v_mfma_f32_16x16x32_bf16 v[8:11], v[168:171], v[216:219], v[8:11]
	v_mfma_f32_16x16x32_bf16 v[52:55], v[172:175], v[188:191], v[52:55]
	v_mfma_f32_16x16x32_bf16 v[48:51], v[180:183], v[188:191], v[48:51]
	v_mfma_f32_16x16x32_bf16 v[36:39], v[172:175], v[196:199], v[36:39]
	v_mfma_f32_16x16x32_bf16 v[32:35], v[180:183], v[196:199], v[32:35]
	v_mfma_f32_16x16x32_bf16 v[20:23], v[172:175], v[204:207], v[20:23]
	v_mfma_f32_16x16x32_bf16 v[16:19], v[180:183], v[204:207], v[16:19]
	v_mfma_f32_16x16x32_bf16 v[4:7], v[172:175], v[212:215], v[4:7]
	v_mfma_f32_16x16x32_bf16 v[0:3], v[180:183], v[212:215], v[0:3]
	v_mfma_f32_16x16x32_bf16 v[52:55], v[176:179], v[192:195], v[52:55]
	v_mfma_f32_16x16x32_bf16 v[48:51], v[184:187], v[192:195], v[48:51]
	v_mfma_f32_16x16x32_bf16 v[36:39], v[176:179], v[200:203], v[36:39]
	v_mfma_f32_16x16x32_bf16 v[32:35], v[184:187], v[200:203], v[32:35]
	v_mfma_f32_16x16x32_bf16 v[20:23], v[176:179], v[208:211], v[20:23]
	v_mfma_f32_16x16x32_bf16 v[16:19], v[184:187], v[208:211], v[16:19]
	v_mfma_f32_16x16x32_bf16 v[4:7], v[176:179], v[216:219], v[4:7]
	v_mfma_f32_16x16x32_bf16 v[0:3], v[184:187], v[216:219], v[0:3]
	s_barrier
	s_add_i32 s65, 0, 0x18000
	s_add_i32 s66, 0, 0x1c000
	v_add_u32_e32 v168, s65, v154
	v_add_u32_e32 v184, s66, v154
	ds_read_b128 v[146:149], v168
	ds_read_b128 v[160:163], v168 offset:1024
	ds_read_b128 v[164:167], v168 offset:2048
	ds_read_b128 v[168:171], v168 offset:3072
	ds_read_b128 v[172:175], v184
	ds_read_b128 v[176:179], v184 offset:1024
	ds_read_b128 v[180:183], v184 offset:2048
	ds_read_b128 v[184:187], v184 offset:3072
	s_add_u32 s36, s42, 0x80000
	s_addc_u32 s37, s43, 0
	s_mov_b32 m0, s48
	v_lshl_add_u64 v[188:189], s[36:37], 0, v[128:129]
	global_load_lds_dwordx4 v[188:189], off
	v_lshl_add_u64 v[188:189], s[36:37], 0, v[132:133]
	s_mov_b32 m0, s49
	s_nop 0
	global_load_lds_dwordx4 v[188:189], off
	ds_read_b128 v[188:191], v158 offset:32768
	ds_read_b128 v[192:195], v158 offset:33792
	ds_read_b128 v[196:199], v158 offset:34816
	ds_read_b128 v[200:203], v158 offset:35840
	ds_read_b128 v[204:207], v158 offset:36864
	ds_read_b128 v[208:211], v158 offset:37888
	ds_read_b128 v[212:215], v158 offset:38912
	ds_read_b128 v[216:219], v158 offset:39936
	s_waitcnt vmcnt(8)
	s_waitcnt lgkmcnt(0)
	s_barrier
	s_waitcnt lgkmcnt(0)
	v_mfma_f32_16x16x32_bf16 v[124:127], v[146:149], v[188:191], v[124:127]
	v_mfma_f32_16x16x32_bf16 v[120:123], v[164:167], v[188:191], v[120:123]
	v_mfma_f32_16x16x32_bf16 v[108:111], v[146:149], v[196:199], v[108:111]
	v_mfma_f32_16x16x32_bf16 v[104:107], v[164:167], v[196:199], v[104:107]
	v_mfma_f32_16x16x32_bf16 v[92:95], v[146:149], v[204:207], v[92:95]
	v_mfma_f32_16x16x32_bf16 v[88:91], v[164:167], v[204:207], v[88:91]
	v_mfma_f32_16x16x32_bf16 v[76:79], v[146:149], v[212:215], v[76:79]
	v_mfma_f32_16x16x32_bf16 v[72:75], v[164:167], v[212:215], v[72:75]
	v_mfma_f32_16x16x32_bf16 v[124:127], v[160:163], v[192:195], v[124:127]
	v_mfma_f32_16x16x32_bf16 v[120:123], v[168:171], v[192:195], v[120:123]
	v_mfma_f32_16x16x32_bf16 v[108:111], v[160:163], v[200:203], v[108:111]
	v_mfma_f32_16x16x32_bf16 v[104:107], v[168:171], v[200:203], v[104:107]
	v_mfma_f32_16x16x32_bf16 v[92:95], v[160:163], v[208:211], v[92:95]
	v_mfma_f32_16x16x32_bf16 v[88:91], v[168:171], v[208:211], v[88:91]
	v_mfma_f32_16x16x32_bf16 v[76:79], v[160:163], v[216:219], v[76:79]
	v_mfma_f32_16x16x32_bf16 v[72:75], v[168:171], v[216:219], v[72:75]
	v_mfma_f32_16x16x32_bf16 v[116:119], v[172:175], v[188:191], v[116:119]
	v_mfma_f32_16x16x32_bf16 v[112:115], v[180:183], v[188:191], v[112:115]
	v_mfma_f32_16x16x32_bf16 v[100:103], v[172:175], v[196:199], v[100:103]
	v_mfma_f32_16x16x32_bf16 v[96:99], v[180:183], v[196:199], v[96:99]
	v_mfma_f32_16x16x32_bf16 v[84:87], v[172:175], v[204:207], v[84:87]
	v_mfma_f32_16x16x32_bf16 v[80:83], v[180:183], v[204:207], v[80:83]
	v_mfma_f32_16x16x32_bf16 v[68:71], v[172:175], v[212:215], v[68:71]
	v_mfma_f32_16x16x32_bf16 v[64:67], v[180:183], v[212:215], v[64:67]
	v_mfma_f32_16x16x32_bf16 v[116:119], v[176:179], v[192:195], v[116:119]
	v_mfma_f32_16x16x32_bf16 v[112:115], v[184:187], v[192:195], v[112:115]
	v_mfma_f32_16x16x32_bf16 v[100:103], v[176:179], v[200:203], v[100:103]
	v_mfma_f32_16x16x32_bf16 v[96:99], v[184:187], v[200:203], v[96:99]
	v_mfma_f32_16x16x32_bf16 v[84:87], v[176:179], v[208:211], v[84:87]
	v_mfma_f32_16x16x32_bf16 v[80:83], v[184:187], v[208:211], v[80:83]
	v_mfma_f32_16x16x32_bf16 v[68:71], v[176:179], v[216:219], v[68:71]
	v_mfma_f32_16x16x32_bf16 v[64:67], v[184:187], v[216:219], v[64:67]
	s_barrier
	s_add_i32 s36, s65, s11
	v_lshl_add_u64 v[150:151], v[150:151], 0, s[14:15]
	s_mov_b32 m0, s36
	s_nop 0
	global_load_lds_dwordx4 v[150:151], off
	s_add_i32 m0, s36, 0x2000
	s_add_u32 s36, s40, 0x80080
	v_lshl_add_u64 v[150:151], v[220:221], 0, s[14:15]
	s_addc_u32 s37, s41, 0
	s_add_i32 s40, s66, s11
	global_load_lds_dwordx4 v[150:151], off
	v_lshl_add_u64 v[150:151], s[36:37], 0, v[130:131]
	s_mov_b32 m0, s40
	s_nop 0
	global_load_lds_dwordx4 v[150:151], off
	v_lshl_add_u64 v[150:151], s[36:37], 0, v[134:135]
	s_add_i32 m0, s40, 0x2000
	s_nop 0
	global_load_lds_dwordx4 v[150:151], off
	v_lshl_add_u64 v[150:151], v[222:223], 0, s[14:15]
	s_mov_b32 m0, s53
	s_nop 0
	global_load_lds_dwordx4 v[150:151], off
	v_lshl_add_u64 v[150:151], v[224:225], 0, s[14:15]
	s_mov_b32 m0, s54
	s_nop 0
	global_load_lds_dwordx4 v[150:151], off
	ds_read_b128 v[188:191], v158 offset:49152
	ds_read_b128 v[192:195], v158 offset:50176
	ds_read_b128 v[196:199], v158 offset:51200
	ds_read_b128 v[200:203], v158 offset:52224
	ds_read_b128 v[204:207], v158 offset:53248
	ds_read_b128 v[208:211], v158 offset:54272
	ds_read_b128 v[212:215], v158 offset:55296
	ds_read_b128 v[216:219], v158 offset:56320
	s_waitcnt vmcnt(8)
	s_waitcnt lgkmcnt(0)
	s_barrier
	s_waitcnt lgkmcnt(0)
	v_mfma_f32_16x16x32_bf16 v[60:63], v[146:149], v[188:191], v[60:63]
	v_mfma_f32_16x16x32_bf16 v[56:59], v[164:167], v[188:191], v[56:59]
	v_mfma_f32_16x16x32_bf16 v[44:47], v[146:149], v[196:199], v[44:47]
	v_mfma_f32_16x16x32_bf16 v[40:43], v[164:167], v[196:199], v[40:43]
	v_mfma_f32_16x16x32_bf16 v[28:31], v[146:149], v[204:207], v[28:31]
	v_mfma_f32_16x16x32_bf16 v[24:27], v[164:167], v[204:207], v[24:27]
	v_mfma_f32_16x16x32_bf16 v[12:15], v[146:149], v[212:215], v[12:15]
	v_mfma_f32_16x16x32_bf16 v[8:11], v[164:167], v[212:215], v[8:11]
	v_mfma_f32_16x16x32_bf16 v[60:63], v[160:163], v[192:195], v[60:63]
	v_mfma_f32_16x16x32_bf16 v[56:59], v[168:171], v[192:195], v[56:59]
	v_mfma_f32_16x16x32_bf16 v[44:47], v[160:163], v[200:203], v[44:47]
	v_mfma_f32_16x16x32_bf16 v[40:43], v[168:171], v[200:203], v[40:43]
	v_mfma_f32_16x16x32_bf16 v[28:31], v[160:163], v[208:211], v[28:31]
	v_mfma_f32_16x16x32_bf16 v[24:27], v[168:171], v[208:211], v[24:27]
	v_mfma_f32_16x16x32_bf16 v[12:15], v[160:163], v[216:219], v[12:15]
	v_mfma_f32_16x16x32_bf16 v[8:11], v[168:171], v[216:219], v[8:11]
	v_mfma_f32_16x16x32_bf16 v[52:55], v[172:175], v[188:191], v[52:55]
	v_mfma_f32_16x16x32_bf16 v[48:51], v[180:183], v[188:191], v[48:51]
	v_mfma_f32_16x16x32_bf16 v[36:39], v[172:175], v[196:199], v[36:39]
	v_mfma_f32_16x16x32_bf16 v[32:35], v[180:183], v[196:199], v[32:35]
	v_mfma_f32_16x16x32_bf16 v[20:23], v[172:175], v[204:207], v[20:23]
	v_mfma_f32_16x16x32_bf16 v[16:19], v[180:183], v[204:207], v[16:19]
	v_mfma_f32_16x16x32_bf16 v[4:7], v[172:175], v[212:215], v[4:7]
	v_mfma_f32_16x16x32_bf16 v[0:3], v[180:183], v[212:215], v[0:3]
	v_mfma_f32_16x16x32_bf16 v[52:55], v[176:179], v[192:195], v[52:55]
	v_mfma_f32_16x16x32_bf16 v[48:51], v[184:187], v[192:195], v[48:51]
	v_mfma_f32_16x16x32_bf16 v[36:39], v[176:179], v[200:203], v[36:39]
	v_mfma_f32_16x16x32_bf16 v[32:35], v[184:187], v[200:203], v[32:35]
	v_mfma_f32_16x16x32_bf16 v[20:23], v[176:179], v[208:211], v[20:23]
	v_mfma_f32_16x16x32_bf16 v[16:19], v[184:187], v[208:211], v[16:19]
	v_mfma_f32_16x16x32_bf16 v[4:7], v[176:179], v[216:219], v[4:7]
	v_mfma_f32_16x16x32_bf16 v[0:3], v[184:187], v[216:219], v[0:3]
	s_barrier
	s_add_i32 s64, s64, 2
	s_add_u32 s62, s62, 0x100
	s_addc_u32 s63, s63, 0
	s_cmp_gt_u32 s64, 29
	s_mov_b64 s[36:37], s[38:39]
	s_cbranch_scc0 .LBB0_387
	s_and_b64 vcc, exec, s[4:5]
	s_cbranch_vccnz .LBB0_392
	s_cmp_gt_i32 s59, 11
	s_mov_b64 s[36:37], -1
	s_cbranch_scc1 .LBB0_393

.LBB0_1117:
	ds_read_b128 v[144:147], v159
	ds_read_b128 v[148:151], v159 offset:1024
	ds_read_b128 v[162:165], v159 offset:2048
	ds_read_b128 v[166:169], v159 offset:3072
	ds_read_b128 v[170:173], v160
	ds_read_b128 v[174:177], v160 offset:1024
	ds_read_b128 v[178:181], v160 offset:2048
	ds_read_b128 v[182:185], v160 offset:3072
	s_add_u32 s48, s46, 0xfff80080
	s_addc_u32 s49, s47, -1
	s_cmp_eq_u32 s63, 28
	s_cselect_b32 s51, s7, s49
	s_cselect_b32 s50, s11, s48
	s_cselect_b32 s49, s37, s62
	s_cselect_b32 s48, s39, s45
	v_lshl_add_u64 v[152:153], s[46:47], 0, v[136:137]
	s_add_i32 m0, s55, 0xc000
	s_nop 0
	global_load_lds_dwordx4 v[152:153], off
	v_lshl_add_u64 v[152:153], s[46:47], 0, v[138:139]
	s_add_i32 m0, s55, 0xe000
	s_nop 0
	global_load_lds_dwordx4 v[152:153], off
	ds_read_b128 v[186:189], v161
	ds_read_b128 v[190:193], v161 offset:1024
	ds_read_b128 v[194:197], v161 offset:2048
	ds_read_b128 v[198:201], v161 offset:3072
	ds_read_b128 v[202:205], v161 offset:4096
	ds_read_b128 v[206:209], v161 offset:5120
	ds_read_b128 v[210:213], v161 offset:6144
	ds_read_b128 v[214:217], v161 offset:7168
	s_waitcnt vmcnt(8)
	s_waitcnt lgkmcnt(0)
	s_barrier
	s_waitcnt lgkmcnt(0)
	v_mfma_f32_16x16x32_bf16 v[124:127], v[144:147], v[186:189], v[124:127]
	v_mfma_f32_16x16x32_bf16 v[120:123], v[162:165], v[186:189], v[120:123]
	v_mfma_f32_16x16x32_bf16 v[108:111], v[144:147], v[194:197], v[108:111]
	v_mfma_f32_16x16x32_bf16 v[104:107], v[162:165], v[194:197], v[104:107]
	v_mfma_f32_16x16x32_bf16 v[92:95], v[144:147], v[202:205], v[92:95]
	v_mfma_f32_16x16x32_bf16 v[88:91], v[162:165], v[202:205], v[88:91]
	v_mfma_f32_16x16x32_bf16 v[76:79], v[144:147], v[210:213], v[76:79]
	v_mfma_f32_16x16x32_bf16 v[72:75], v[162:165], v[210:213], v[72:75]
	v_mfma_f32_16x16x32_bf16 v[124:127], v[148:151], v[190:193], v[124:127]
	v_mfma_f32_16x16x32_bf16 v[120:123], v[166:169], v[190:193], v[120:123]
	v_mfma_f32_16x16x32_bf16 v[108:111], v[148:151], v[198:201], v[108:111]
	v_mfma_f32_16x16x32_bf16 v[104:107], v[166:169], v[198:201], v[104:107]
	v_mfma_f32_16x16x32_bf16 v[92:95], v[148:151], v[206:209], v[92:95]
	v_mfma_f32_16x16x32_bf16 v[88:91], v[166:169], v[206:209], v[88:91]
	v_mfma_f32_16x16x32_bf16 v[76:79], v[148:151], v[214:217], v[76:79]
	v_mfma_f32_16x16x32_bf16 v[72:75], v[166:169], v[214:217], v[72:75]
	v_mfma_f32_16x16x32_bf16 v[116:119], v[170:173], v[186:189], v[116:119]
	v_mfma_f32_16x16x32_bf16 v[112:115], v[178:181], v[186:189], v[112:115]
	v_mfma_f32_16x16x32_bf16 v[100:103], v[170:173], v[194:197], v[100:103]
	v_mfma_f32_16x16x32_bf16 v[96:99], v[178:181], v[194:197], v[96:99]
	v_mfma_f32_16x16x32_bf16 v[84:87], v[170:173], v[202:205], v[84:87]
	v_mfma_f32_16x16x32_bf16 v[80:83], v[178:181], v[202:205], v[80:83]
	v_mfma_f32_16x16x32_bf16 v[68:71], v[170:173], v[210:213], v[68:71]
	v_mfma_f32_16x16x32_bf16 v[64:67], v[178:181], v[210:213], v[64:67]
	v_mfma_f32_16x16x32_bf16 v[116:119], v[174:177], v[190:193], v[116:119]
	v_mfma_f32_16x16x32_bf16 v[112:115], v[182:185], v[190:193], v[112:115]
	v_mfma_f32_16x16x32_bf16 v[100:103], v[174:177], v[198:201], v[100:103]
	v_mfma_f32_16x16x32_bf16 v[96:99], v[182:185], v[198:201], v[96:99]
	v_mfma_f32_16x16x32_bf16 v[84:87], v[174:177], v[206:209], v[84:87]
	v_mfma_f32_16x16x32_bf16 v[80:83], v[182:185], v[206:209], v[80:83]
	v_mfma_f32_16x16x32_bf16 v[68:71], v[174:177], v[214:217], v[68:71]
	v_mfma_f32_16x16x32_bf16 v[64:67], v[182:185], v[214:217], v[64:67]
	s_barrier
	s_add_i32 s64, s60, s21
	v_lshl_add_u64 v[152:153], s[48:49], 0, v[130:131]
	s_mov_b32 m0, s64
	v_lshl_add_u64 v[218:219], s[48:49], 0, v[134:135]
	global_load_lds_dwordx4 v[152:153], off
	s_add_i32 m0, s64, 0x2000
	s_add_u32 s64, s48, 0x80000
	s_addc_u32 s65, s49, 0
	s_add_i32 s66, s61, s21
	global_load_lds_dwordx4 v[218:219], off
	v_lshl_add_u64 v[186:187], s[64:65], 0, v[130:131]
	s_mov_b32 m0, s66
	v_lshl_add_u64 v[220:221], s[50:51], 0, v[128:129]
	global_load_lds_dwordx4 v[186:187], off
	v_lshl_add_u64 v[186:187], s[64:65], 0, v[134:135]
	s_add_i32 m0, s66, 0x2000
	v_lshl_add_u64 v[222:223], s[50:51], 0, v[132:133]
	global_load_lds_dwordx4 v[186:187], off
	s_mov_b32 m0, s55
	s_nop 0
	global_load_lds_dwordx4 v[220:221], off
	s_mov_b32 m0, s56
	s_nop 0
	global_load_lds_dwordx4 v[222:223], off
	ds_read_b128 v[186:189], v161 offset:16384
	ds_read_b128 v[190:193], v161 offset:17408
	ds_read_b128 v[194:197], v161 offset:18432
	ds_read_b128 v[198:201], v161 offset:19456
	ds_read_b128 v[202:205], v161 offset:20480
	ds_read_b128 v[206:209], v161 offset:21504
	ds_read_b128 v[210:213], v161 offset:22528
	ds_read_b128 v[214:217], v161 offset:23552
	s_waitcnt vmcnt(8)
	s_waitcnt lgkmcnt(0)
	s_barrier
	s_waitcnt lgkmcnt(0)
	v_mfma_f32_16x16x32_bf16 v[60:63], v[144:147], v[186:189], v[60:63]
	v_mfma_f32_16x16x32_bf16 v[56:59], v[162:165], v[186:189], v[56:59]
	v_mfma_f32_16x16x32_bf16 v[44:47], v[144:147], v[194:197], v[44:47]
	v_mfma_f32_16x16x32_bf16 v[40:43], v[162:165], v[194:197], v[40:43]
	v_mfma_f32_16x16x32_bf16 v[28:31], v[144:147], v[202:205], v[28:31]
	v_mfma_f32_16x16x32_bf16 v[24:27], v[162:165], v[202:205], v[24:27]
	v_mfma_f32_16x16x32_bf16 v[12:15], v[144:147], v[210:213], v[12:15]
	v_mfma_f32_16x16x32_bf16 v[8:11], v[162:165], v[210:213], v[8:11]
	v_mfma_f32_16x16x32_bf16 v[60:63], v[148:151], v[190:193], v[60:63]
	v_mfma_f32_16x16x32_bf16 v[56:59], v[166:169], v[190:193], v[56:59]
	v_mfma_f32_16x16x32_bf16 v[44:47], v[148:151], v[198:201], v[44:47]
	v_mfma_f32_16x16x32_bf16 v[40:43], v[166:169], v[198:201], v[40:43]
	v_mfma_f32_16x16x32_bf16 v[28:31], v[148:151], v[206:209], v[28:31]
	v_mfma_f32_16x16x32_bf16 v[24:27], v[166:169], v[206:209], v[24:27]
	v_mfma_f32_16x16x32_bf16 v[12:15], v[148:151], v[214:217], v[12:15]
	v_mfma_f32_16x16x32_bf16 v[8:11], v[166:169], v[214:217], v[8:11]
	v_mfma_f32_16x16x32_bf16 v[52:55], v[170:173], v[186:189], v[52:55]
	v_mfma_f32_16x16x32_bf16 v[48:51], v[178:181], v[186:189], v[48:51]
	v_mfma_f32_16x16x32_bf16 v[36:39], v[170:173], v[194:197], v[36:39]
	v_mfma_f32_16x16x32_bf16 v[32:35], v[178:181], v[194:197], v[32:35]
	v_mfma_f32_16x16x32_bf16 v[20:23], v[170:173], v[202:205], v[20:23]
	v_mfma_f32_16x16x32_bf16 v[16:19], v[178:181], v[202:205], v[16:19]
	v_mfma_f32_16x16x32_bf16 v[4:7], v[170:173], v[210:213], v[4:7]
	v_mfma_f32_16x16x32_bf16 v[0:3], v[178:181], v[210:213], v[0:3]
	v_mfma_f32_16x16x32_bf16 v[52:55], v[174:177], v[190:193], v[52:55]
	v_mfma_f32_16x16x32_bf16 v[48:51], v[182:185], v[190:193], v[48:51]
	v_mfma_f32_16x16x32_bf16 v[36:39], v[174:177], v[198:201], v[36:39]
	v_mfma_f32_16x16x32_bf16 v[32:35], v[182:185], v[198:201], v[32:35]
	v_mfma_f32_16x16x32_bf16 v[20:23], v[174:177], v[206:209], v[20:23]
	v_mfma_f32_16x16x32_bf16 v[16:19], v[182:185], v[206:209], v[16:19]
	v_mfma_f32_16x16x32_bf16 v[4:7], v[174:177], v[214:217], v[4:7]
	v_mfma_f32_16x16x32_bf16 v[0:3], v[182:185], v[214:217], v[0:3]
	s_barrier
	s_add_i32 s64, 0, 0x18000
	s_add_i32 s65, 0, 0x1c000
	v_add_u32_e32 v166, s64, v154
	v_add_u32_e32 v182, s65, v154
	ds_read_b128 v[144:147], v166
	ds_read_b128 v[148:151], v166 offset:1024
	ds_read_b128 v[162:165], v166 offset:2048
	ds_read_b128 v[166:169], v166 offset:3072
	ds_read_b128 v[170:173], v182
	ds_read_b128 v[174:177], v182 offset:1024
	ds_read_b128 v[178:181], v182 offset:2048
	ds_read_b128 v[182:185], v182 offset:3072
	s_add_u32 s50, s50, 0x80000
	s_addc_u32 s51, s51, 0
	s_mov_b32 m0, s57
	v_lshl_add_u64 v[186:187], s[50:51], 0, v[128:129]
	global_load_lds_dwordx4 v[186:187], off
	v_lshl_add_u64 v[186:187], s[50:51], 0, v[132:133]
	s_mov_b32 m0, s58
	s_nop 0
	global_load_lds_dwordx4 v[186:187], off
	ds_read_b128 v[186:189], v161 offset:32768
	ds_read_b128 v[190:193], v161 offset:33792
	ds_read_b128 v[194:197], v161 offset:34816
	ds_read_b128 v[198:201], v161 offset:35840
	ds_read_b128 v[202:205], v161 offset:36864
	ds_read_b128 v[206:209], v161 offset:37888
	ds_read_b128 v[210:213], v161 offset:38912
	ds_read_b128 v[214:217], v161 offset:39936
	s_waitcnt vmcnt(8)
	s_waitcnt lgkmcnt(0)
	s_barrier
	s_waitcnt lgkmcnt(0)
	v_mfma_f32_16x16x32_bf16 v[124:127], v[144:147], v[186:189], v[124:127]
	v_mfma_f32_16x16x32_bf16 v[120:123], v[162:165], v[186:189], v[120:123]
	v_mfma_f32_16x16x32_bf16 v[108:111], v[144:147], v[194:197], v[108:111]
	v_mfma_f32_16x16x32_bf16 v[104:107], v[162:165], v[194:197], v[104:107]
	v_mfma_f32_16x16x32_bf16 v[92:95], v[144:147], v[202:205], v[92:95]
	v_mfma_f32_16x16x32_bf16 v[88:91], v[162:165], v[202:205], v[88:91]
	v_mfma_f32_16x16x32_bf16 v[76:79], v[144:147], v[210:213], v[76:79]
	v_mfma_f32_16x16x32_bf16 v[72:75], v[162:165], v[210:213], v[72:75]
	v_mfma_f32_16x16x32_bf16 v[124:127], v[148:151], v[190:193], v[124:127]
	v_mfma_f32_16x16x32_bf16 v[120:123], v[166:169], v[190:193], v[120:123]
	v_mfma_f32_16x16x32_bf16 v[108:111], v[148:151], v[198:201], v[108:111]
	v_mfma_f32_16x16x32_bf16 v[104:107], v[166:169], v[198:201], v[104:107]
	v_mfma_f32_16x16x32_bf16 v[92:95], v[148:151], v[206:209], v[92:95]
	v_mfma_f32_16x16x32_bf16 v[88:91], v[166:169], v[206:209], v[88:91]
	v_mfma_f32_16x16x32_bf16 v[76:79], v[148:151], v[214:217], v[76:79]
	v_mfma_f32_16x16x32_bf16 v[72:75], v[166:169], v[214:217], v[72:75]
	v_mfma_f32_16x16x32_bf16 v[116:119], v[170:173], v[186:189], v[116:119]
	v_mfma_f32_16x16x32_bf16 v[112:115], v[178:181], v[186:189], v[112:115]
	v_mfma_f32_16x16x32_bf16 v[100:103], v[170:173], v[194:197], v[100:103]
	v_mfma_f32_16x16x32_bf16 v[96:99], v[178:181], v[194:197], v[96:99]
	v_mfma_f32_16x16x32_bf16 v[84:87], v[170:173], v[202:205], v[84:87]
	v_mfma_f32_16x16x32_bf16 v[80:83], v[178:181], v[202:205], v[80:83]
	v_mfma_f32_16x16x32_bf16 v[68:71], v[170:173], v[210:213], v[68:71]
	v_mfma_f32_16x16x32_bf16 v[64:67], v[178:181], v[210:213], v[64:67]
	v_mfma_f32_16x16x32_bf16 v[116:119], v[174:177], v[190:193], v[116:119]
	v_mfma_f32_16x16x32_bf16 v[112:115], v[182:185], v[190:193], v[112:115]
	v_mfma_f32_16x16x32_bf16 v[100:103], v[174:177], v[198:201], v[100:103]
	v_mfma_f32_16x16x32_bf16 v[96:99], v[182:185], v[198:201], v[96:99]
	v_mfma_f32_16x16x32_bf16 v[84:87], v[174:177], v[206:209], v[84:87]
	v_mfma_f32_16x16x32_bf16 v[80:83], v[182:185], v[206:209], v[80:83]
	v_mfma_f32_16x16x32_bf16 v[68:71], v[174:177], v[214:217], v[68:71]
	v_mfma_f32_16x16x32_bf16 v[64:67], v[182:185], v[214:217], v[64:67]
	s_barrier
	s_add_i32 s50, s64, s21
	v_lshl_add_u64 v[152:153], v[152:153], 0, s[30:31]
	s_mov_b32 m0, s50
	s_nop 0
	global_load_lds_dwordx4 v[152:153], off
	s_add_i32 m0, s50, 0x2000
	s_add_u32 s48, s48, 0x80080
	v_lshl_add_u64 v[152:153], v[218:219], 0, s[30:31]
	s_addc_u32 s49, s49, 0
	s_add_i32 s50, s65, s21
	global_load_lds_dwordx4 v[152:153], off
	v_lshl_add_u64 v[152:153], s[48:49], 0, v[130:131]
	s_mov_b32 m0, s50
	s_nop 0
	global_load_lds_dwordx4 v[152:153], off
	v_lshl_add_u64 v[152:153], s[48:49], 0, v[134:135]
	s_add_i32 m0, s50, 0x2000
	s_nop 0
	global_load_lds_dwordx4 v[152:153], off
	v_lshl_add_u64 v[152:153], v[220:221], 0, s[30:31]
	s_mov_b32 m0, s26
	s_nop 0
	global_load_lds_dwordx4 v[152:153], off
	v_lshl_add_u64 v[152:153], v[222:223], 0, s[30:31]
	s_mov_b32 m0, s27
	s_nop 0
	global_load_lds_dwordx4 v[152:153], off
	ds_read_b128 v[186:189], v161 offset:49152
	ds_read_b128 v[190:193], v161 offset:50176
	ds_read_b128 v[194:197], v161 offset:51200
	ds_read_b128 v[198:201], v161 offset:52224
	ds_read_b128 v[202:205], v161 offset:53248
	ds_read_b128 v[206:209], v161 offset:54272
	ds_read_b128 v[210:213], v161 offset:55296
	ds_read_b128 v[214:217], v161 offset:56320
	s_waitcnt vmcnt(8)
	s_waitcnt lgkmcnt(0)
	s_barrier
	s_waitcnt lgkmcnt(0)
	v_mfma_f32_16x16x32_bf16 v[60:63], v[144:147], v[186:189], v[60:63]
	v_mfma_f32_16x16x32_bf16 v[56:59], v[162:165], v[186:189], v[56:59]
	v_mfma_f32_16x16x32_bf16 v[44:47], v[144:147], v[194:197], v[44:47]
	v_mfma_f32_16x16x32_bf16 v[40:43], v[162:165], v[194:197], v[40:43]
	v_mfma_f32_16x16x32_bf16 v[28:31], v[144:147], v[202:205], v[28:31]
	v_mfma_f32_16x16x32_bf16 v[24:27], v[162:165], v[202:205], v[24:27]
	v_mfma_f32_16x16x32_bf16 v[12:15], v[144:147], v[210:213], v[12:15]
	v_mfma_f32_16x16x32_bf16 v[8:11], v[162:165], v[210:213], v[8:11]
	v_mfma_f32_16x16x32_bf16 v[60:63], v[148:151], v[190:193], v[60:63]
	v_mfma_f32_16x16x32_bf16 v[56:59], v[166:169], v[190:193], v[56:59]
	v_mfma_f32_16x16x32_bf16 v[44:47], v[148:151], v[198:201], v[44:47]
	v_mfma_f32_16x16x32_bf16 v[40:43], v[166:169], v[198:201], v[40:43]
	v_mfma_f32_16x16x32_bf16 v[28:31], v[148:151], v[206:209], v[28:31]
	v_mfma_f32_16x16x32_bf16 v[24:27], v[166:169], v[206:209], v[24:27]
	v_mfma_f32_16x16x32_bf16 v[12:15], v[148:151], v[214:217], v[12:15]
	v_mfma_f32_16x16x32_bf16 v[8:11], v[166:169], v[214:217], v[8:11]
	v_mfma_f32_16x16x32_bf16 v[52:55], v[170:173], v[186:189], v[52:55]
	v_mfma_f32_16x16x32_bf16 v[48:51], v[178:181], v[186:189], v[48:51]
	v_mfma_f32_16x16x32_bf16 v[36:39], v[170:173], v[194:197], v[36:39]
	v_mfma_f32_16x16x32_bf16 v[32:35], v[178:181], v[194:197], v[32:35]
	v_mfma_f32_16x16x32_bf16 v[20:23], v[170:173], v[202:205], v[20:23]
	v_mfma_f32_16x16x32_bf16 v[16:19], v[178:181], v[202:205], v[16:19]
	v_mfma_f32_16x16x32_bf16 v[4:7], v[170:173], v[210:213], v[4:7]
	v_mfma_f32_16x16x32_bf16 v[0:3], v[178:181], v[210:213], v[0:3]
	v_mfma_f32_16x16x32_bf16 v[52:55], v[174:177], v[190:193], v[52:55]
	v_mfma_f32_16x16x32_bf16 v[48:51], v[182:185], v[190:193], v[48:51]
	v_mfma_f32_16x16x32_bf16 v[36:39], v[174:177], v[198:201], v[36:39]
	v_mfma_f32_16x16x32_bf16 v[32:35], v[182:185], v[198:201], v[32:35]
	v_mfma_f32_16x16x32_bf16 v[20:23], v[174:177], v[206:209], v[20:23]
	v_mfma_f32_16x16x32_bf16 v[16:19], v[182:185], v[206:209], v[16:19]
	v_mfma_f32_16x16x32_bf16 v[4:7], v[174:177], v[214:217], v[4:7]
	v_mfma_f32_16x16x32_bf16 v[0:3], v[182:185], v[214:217], v[0:3]
	s_barrier
	s_add_i32 s63, s63, 2
	s_add_u32 s46, s46, 0x100
	s_addc_u32 s47, s47, 0
	s_add_u32 s45, s45, 0x100
	s_addc_u32 s62, s62, 0
	s_cmp_gt_u32 s63, 29
	s_cbranch_scc0 .LBB0_1117
	s_and_b64 vcc, exec, s[16:17]
	s_cbranch_vccz .LBB0_1120
	s_barrier

.LBB0_1240:
	ds_read_b128 v[144:147], v153
	ds_read_b128 v[158:161], v153 offset:1024
	ds_read_b128 v[162:165], v153 offset:2048
	ds_read_b128 v[166:169], v153 offset:3072
	ds_read_b128 v[170:173], v154
	ds_read_b128 v[174:177], v154 offset:1024
	ds_read_b128 v[178:181], v154 offset:2048
	ds_read_b128 v[182:185], v154 offset:3072
	s_add_u32 s40, s38, 0x100
	s_addc_u32 s41, s39, 0
	s_cmp_eq_u32 s61, 28
	s_cselect_b32 s45, s29, s41
	s_cselect_b32 s44, s57, s40
	s_cselect_b32 s43, s19, s60
	s_cselect_b32 s42, s58, s59
	v_lshl_add_u64 v[148:149], s[38:39], 0, v[136:137]
	s_add_i32 m0, s37, 0xc000
	s_nop 0
	global_load_lds_dwordx4 v[148:149], off
	v_lshl_add_u64 v[148:149], s[38:39], 0, v[138:139]
	s_add_i32 m0, s37, 0xe000
	s_nop 0
	global_load_lds_dwordx4 v[148:149], off
	ds_read_b128 v[186:189], v155
	ds_read_b128 v[190:193], v155 offset:1024
	ds_read_b128 v[194:197], v155 offset:2048
	ds_read_b128 v[198:201], v155 offset:3072
	ds_read_b128 v[202:205], v155 offset:4096
	ds_read_b128 v[206:209], v155 offset:5120
	ds_read_b128 v[210:213], v155 offset:6144
	ds_read_b128 v[214:217], v155 offset:7168
	s_waitcnt vmcnt(8)
	s_waitcnt lgkmcnt(0)
	s_barrier
	s_waitcnt lgkmcnt(0)
	v_mfma_f32_16x16x32_bf16 v[124:127], v[144:147], v[186:189], v[124:127]
	v_mfma_f32_16x16x32_bf16 v[120:123], v[162:165], v[186:189], v[120:123]
	v_mfma_f32_16x16x32_bf16 v[108:111], v[144:147], v[194:197], v[108:111]
	v_mfma_f32_16x16x32_bf16 v[104:107], v[162:165], v[194:197], v[104:107]
	v_mfma_f32_16x16x32_bf16 v[92:95], v[144:147], v[202:205], v[92:95]
	v_mfma_f32_16x16x32_bf16 v[88:91], v[162:165], v[202:205], v[88:91]
	v_mfma_f32_16x16x32_bf16 v[76:79], v[144:147], v[210:213], v[76:79]
	v_mfma_f32_16x16x32_bf16 v[72:75], v[162:165], v[210:213], v[72:75]
	v_mfma_f32_16x16x32_bf16 v[124:127], v[158:161], v[190:193], v[124:127]
	v_mfma_f32_16x16x32_bf16 v[120:123], v[166:169], v[190:193], v[120:123]
	v_mfma_f32_16x16x32_bf16 v[108:111], v[158:161], v[198:201], v[108:111]
	v_mfma_f32_16x16x32_bf16 v[104:107], v[166:169], v[198:201], v[104:107]
	v_mfma_f32_16x16x32_bf16 v[92:95], v[158:161], v[206:209], v[92:95]
	v_mfma_f32_16x16x32_bf16 v[88:91], v[166:169], v[206:209], v[88:91]
	v_mfma_f32_16x16x32_bf16 v[76:79], v[158:161], v[214:217], v[76:79]
	v_mfma_f32_16x16x32_bf16 v[72:75], v[166:169], v[214:217], v[72:75]
	v_mfma_f32_16x16x32_bf16 v[116:119], v[170:173], v[186:189], v[116:119]
	v_mfma_f32_16x16x32_bf16 v[112:115], v[178:181], v[186:189], v[112:115]
	v_mfma_f32_16x16x32_bf16 v[100:103], v[170:173], v[194:197], v[100:103]
	v_mfma_f32_16x16x32_bf16 v[96:99], v[178:181], v[194:197], v[96:99]
	v_mfma_f32_16x16x32_bf16 v[84:87], v[170:173], v[202:205], v[84:87]
	v_mfma_f32_16x16x32_bf16 v[80:83], v[178:181], v[202:205], v[80:83]
	v_mfma_f32_16x16x32_bf16 v[68:71], v[170:173], v[210:213], v[68:71]
	v_mfma_f32_16x16x32_bf16 v[64:67], v[178:181], v[210:213], v[64:67]
	v_mfma_f32_16x16x32_bf16 v[116:119], v[174:177], v[190:193], v[116:119]
	v_mfma_f32_16x16x32_bf16 v[112:115], v[182:185], v[190:193], v[112:115]
	v_mfma_f32_16x16x32_bf16 v[100:103], v[174:177], v[198:201], v[100:103]
	v_mfma_f32_16x16x32_bf16 v[96:99], v[182:185], v[198:201], v[96:99]
	v_mfma_f32_16x16x32_bf16 v[84:87], v[174:177], v[206:209], v[84:87]
	v_mfma_f32_16x16x32_bf16 v[80:83], v[182:185], v[206:209], v[80:83]
	v_mfma_f32_16x16x32_bf16 v[68:71], v[174:177], v[214:217], v[68:71]
	v_mfma_f32_16x16x32_bf16 v[64:67], v[182:185], v[214:217], v[64:67]
	s_barrier
	s_add_i32 s38, s54, s21
	v_lshl_add_u64 v[148:149], s[42:43], 0, v[132:133]
	s_mov_b32 m0, s38
	v_lshl_add_u64 v[218:219], s[42:43], 0, v[128:129]
	global_load_lds_dwordx4 v[148:149], off
	s_add_i32 m0, s38, 0x2000
	s_add_u32 s38, s42, 0x80000
	s_addc_u32 s39, s43, 0
	s_add_i32 s62, s55, s21
	global_load_lds_dwordx4 v[218:219], off
	v_lshl_add_u64 v[186:187], s[38:39], 0, v[132:133]
	s_mov_b32 m0, s62
	v_lshl_add_u64 v[220:221], s[44:45], 0, v[134:135]
	global_load_lds_dwordx4 v[186:187], off
	v_lshl_add_u64 v[186:187], s[38:39], 0, v[128:129]
	s_add_i32 m0, s62, 0x2000
	v_lshl_add_u64 v[222:223], s[44:45], 0, v[130:131]
	global_load_lds_dwordx4 v[186:187], off
	s_mov_b32 m0, s37
	s_nop 0
	global_load_lds_dwordx4 v[220:221], off
	s_mov_b32 m0, s47
	s_nop 0
	global_load_lds_dwordx4 v[222:223], off
	ds_read_b128 v[186:189], v155 offset:16384
	ds_read_b128 v[190:193], v155 offset:17408
	ds_read_b128 v[194:197], v155 offset:18432
	ds_read_b128 v[198:201], v155 offset:19456
	ds_read_b128 v[202:205], v155 offset:20480
	ds_read_b128 v[206:209], v155 offset:21504
	ds_read_b128 v[210:213], v155 offset:22528
	ds_read_b128 v[214:217], v155 offset:23552
	s_waitcnt vmcnt(8)
	s_waitcnt lgkmcnt(0)
	s_barrier
	s_waitcnt lgkmcnt(0)
	v_mfma_f32_16x16x32_bf16 v[60:63], v[144:147], v[186:189], v[60:63]
	v_mfma_f32_16x16x32_bf16 v[56:59], v[162:165], v[186:189], v[56:59]
	v_mfma_f32_16x16x32_bf16 v[44:47], v[144:147], v[194:197], v[44:47]
	v_mfma_f32_16x16x32_bf16 v[40:43], v[162:165], v[194:197], v[40:43]
	v_mfma_f32_16x16x32_bf16 v[28:31], v[144:147], v[202:205], v[28:31]
	v_mfma_f32_16x16x32_bf16 v[24:27], v[162:165], v[202:205], v[24:27]
	v_mfma_f32_16x16x32_bf16 v[12:15], v[144:147], v[210:213], v[12:15]
	v_mfma_f32_16x16x32_bf16 v[8:11], v[162:165], v[210:213], v[8:11]
	v_mfma_f32_16x16x32_bf16 v[60:63], v[158:161], v[190:193], v[60:63]
	v_mfma_f32_16x16x32_bf16 v[56:59], v[166:169], v[190:193], v[56:59]
	v_mfma_f32_16x16x32_bf16 v[44:47], v[158:161], v[198:201], v[44:47]
	v_mfma_f32_16x16x32_bf16 v[40:43], v[166:169], v[198:201], v[40:43]
	v_mfma_f32_16x16x32_bf16 v[28:31], v[158:161], v[206:209], v[28:31]
	v_mfma_f32_16x16x32_bf16 v[24:27], v[166:169], v[206:209], v[24:27]
	v_mfma_f32_16x16x32_bf16 v[12:15], v[158:161], v[214:217], v[12:15]
	v_mfma_f32_16x16x32_bf16 v[8:11], v[166:169], v[214:217], v[8:11]
	v_mfma_f32_16x16x32_bf16 v[52:55], v[170:173], v[186:189], v[52:55]
	v_mfma_f32_16x16x32_bf16 v[48:51], v[178:181], v[186:189], v[48:51]
	v_mfma_f32_16x16x32_bf16 v[36:39], v[170:173], v[194:197], v[36:39]
	v_mfma_f32_16x16x32_bf16 v[32:35], v[178:181], v[194:197], v[32:35]
	v_mfma_f32_16x16x32_bf16 v[20:23], v[170:173], v[202:205], v[20:23]
	v_mfma_f32_16x16x32_bf16 v[16:19], v[178:181], v[202:205], v[16:19]
	v_mfma_f32_16x16x32_bf16 v[4:7], v[170:173], v[210:213], v[4:7]
	v_mfma_f32_16x16x32_bf16 v[0:3], v[178:181], v[210:213], v[0:3]
	v_mfma_f32_16x16x32_bf16 v[52:55], v[174:177], v[190:193], v[52:55]
	v_mfma_f32_16x16x32_bf16 v[48:51], v[182:185], v[190:193], v[48:51]
	v_mfma_f32_16x16x32_bf16 v[36:39], v[174:177], v[198:201], v[36:39]
	v_mfma_f32_16x16x32_bf16 v[32:35], v[182:185], v[198:201], v[32:35]
	v_mfma_f32_16x16x32_bf16 v[20:23], v[174:177], v[206:209], v[20:23]
	v_mfma_f32_16x16x32_bf16 v[16:19], v[182:185], v[206:209], v[16:19]
	v_mfma_f32_16x16x32_bf16 v[4:7], v[174:177], v[214:217], v[4:7]
	v_mfma_f32_16x16x32_bf16 v[0:3], v[182:185], v[214:217], v[0:3]
	s_barrier
	s_add_i32 s62, 0, 0x18000
	v_add_u32_e32 v157, s62, v150
	s_add_i32 s63, 0, 0x1c000
	ds_read_b128 v[144:147], v157
	ds_read_b128 v[158:161], v157 offset:1024
	ds_read_b128 v[162:165], v157 offset:2048
	ds_read_b128 v[166:169], v157 offset:3072
	v_add_u32_e32 v157, s63, v150
	ds_read_b128 v[170:173], v157
	ds_read_b128 v[174:177], v157 offset:1024
	ds_read_b128 v[178:181], v157 offset:2048
	ds_read_b128 v[182:185], v157 offset:3072
	s_add_u32 s38, s44, 0x80000
	s_addc_u32 s39, s45, 0
	s_mov_b32 m0, s48
	v_lshl_add_u64 v[186:187], s[38:39], 0, v[134:135]
	global_load_lds_dwordx4 v[186:187], off
	v_lshl_add_u64 v[186:187], s[38:39], 0, v[130:131]
	s_mov_b32 m0, s49
	s_nop 0
	global_load_lds_dwordx4 v[186:187], off
	ds_read_b128 v[186:189], v155 offset:32768
	ds_read_b128 v[190:193], v155 offset:33792
	ds_read_b128 v[194:197], v155 offset:34816
	ds_read_b128 v[198:201], v155 offset:35840
	ds_read_b128 v[202:205], v155 offset:36864
	ds_read_b128 v[206:209], v155 offset:37888
	ds_read_b128 v[210:213], v155 offset:38912
	ds_read_b128 v[214:217], v155 offset:39936
	s_waitcnt vmcnt(8)
	s_waitcnt lgkmcnt(0)
	s_barrier
	s_waitcnt lgkmcnt(0)
	v_mfma_f32_16x16x32_bf16 v[124:127], v[144:147], v[186:189], v[124:127]
	v_mfma_f32_16x16x32_bf16 v[120:123], v[162:165], v[186:189], v[120:123]
	v_mfma_f32_16x16x32_bf16 v[108:111], v[144:147], v[194:197], v[108:111]
	v_mfma_f32_16x16x32_bf16 v[104:107], v[162:165], v[194:197], v[104:107]
	v_mfma_f32_16x16x32_bf16 v[92:95], v[144:147], v[202:205], v[92:95]
	v_mfma_f32_16x16x32_bf16 v[88:91], v[162:165], v[202:205], v[88:91]
	v_mfma_f32_16x16x32_bf16 v[76:79], v[144:147], v[210:213], v[76:79]
	v_mfma_f32_16x16x32_bf16 v[72:75], v[162:165], v[210:213], v[72:75]
	v_mfma_f32_16x16x32_bf16 v[124:127], v[158:161], v[190:193], v[124:127]
	v_mfma_f32_16x16x32_bf16 v[120:123], v[166:169], v[190:193], v[120:123]
	v_mfma_f32_16x16x32_bf16 v[108:111], v[158:161], v[198:201], v[108:111]
	v_mfma_f32_16x16x32_bf16 v[104:107], v[166:169], v[198:201], v[104:107]
	v_mfma_f32_16x16x32_bf16 v[92:95], v[158:161], v[206:209], v[92:95]
	v_mfma_f32_16x16x32_bf16 v[88:91], v[166:169], v[206:209], v[88:91]
	v_mfma_f32_16x16x32_bf16 v[76:79], v[158:161], v[214:217], v[76:79]
	v_mfma_f32_16x16x32_bf16 v[72:75], v[166:169], v[214:217], v[72:75]
	v_mfma_f32_16x16x32_bf16 v[116:119], v[170:173], v[186:189], v[116:119]
	v_mfma_f32_16x16x32_bf16 v[112:115], v[178:181], v[186:189], v[112:115]
	v_mfma_f32_16x16x32_bf16 v[100:103], v[170:173], v[194:197], v[100:103]
	v_mfma_f32_16x16x32_bf16 v[96:99], v[178:181], v[194:197], v[96:99]
	v_mfma_f32_16x16x32_bf16 v[84:87], v[170:173], v[202:205], v[84:87]
	v_mfma_f32_16x16x32_bf16 v[80:83], v[178:181], v[202:205], v[80:83]
	v_mfma_f32_16x16x32_bf16 v[68:71], v[170:173], v[210:213], v[68:71]
	v_mfma_f32_16x16x32_bf16 v[64:67], v[178:181], v[210:213], v[64:67]
	v_mfma_f32_16x16x32_bf16 v[116:119], v[174:177], v[190:193], v[116:119]
	v_mfma_f32_16x16x32_bf16 v[112:115], v[182:185], v[190:193], v[112:115]
	v_mfma_f32_16x16x32_bf16 v[100:103], v[174:177], v[198:201], v[100:103]
	v_mfma_f32_16x16x32_bf16 v[96:99], v[182:185], v[198:201], v[96:99]
	v_mfma_f32_16x16x32_bf16 v[84:87], v[174:177], v[206:209], v[84:87]
	v_mfma_f32_16x16x32_bf16 v[80:83], v[182:185], v[206:209], v[80:83]
	v_mfma_f32_16x16x32_bf16 v[68:71], v[174:177], v[214:217], v[68:71]
	v_mfma_f32_16x16x32_bf16 v[64:67], v[182:185], v[214:217], v[64:67]
	s_barrier
	s_add_i32 s38, s62, s21
	v_lshl_add_u64 v[148:149], v[148:149], 0, s[16:17]
	s_mov_b32 m0, s38
	s_nop 0
	global_load_lds_dwordx4 v[148:149], off
	s_add_i32 m0, s38, 0x2000
	s_add_u32 s38, s42, 0x80080
	v_lshl_add_u64 v[148:149], v[218:219], 0, s[16:17]
	s_addc_u32 s39, s43, 0
	s_add_i32 s42, s63, s21
	global_load_lds_dwordx4 v[148:149], off
	v_lshl_add_u64 v[148:149], s[38:39], 0, v[132:133]
	s_mov_b32 m0, s42
	s_nop 0
	global_load_lds_dwordx4 v[148:149], off
	v_lshl_add_u64 v[148:149], s[38:39], 0, v[128:129]
	s_add_i32 m0, s42, 0x2000
	s_nop 0
	global_load_lds_dwordx4 v[148:149], off
	v_lshl_add_u64 v[148:149], v[220:221], 0, s[16:17]
	s_mov_b32 m0, s51
	s_nop 0
	global_load_lds_dwordx4 v[148:149], off
	v_lshl_add_u64 v[148:149], v[222:223], 0, s[16:17]
	s_mov_b32 m0, s52
	s_nop 0
	global_load_lds_dwordx4 v[148:149], off
	ds_read_b128 v[186:189], v155 offset:49152
	ds_read_b128 v[190:193], v155 offset:50176
	ds_read_b128 v[194:197], v155 offset:51200
	ds_read_b128 v[198:201], v155 offset:52224
	ds_read_b128 v[202:205], v155 offset:53248
	ds_read_b128 v[206:209], v155 offset:54272
	ds_read_b128 v[210:213], v155 offset:55296
	ds_read_b128 v[214:217], v155 offset:56320
	s_waitcnt vmcnt(8)
	s_waitcnt lgkmcnt(0)
	s_barrier
	s_waitcnt lgkmcnt(0)
	v_mfma_f32_16x16x32_bf16 v[60:63], v[144:147], v[186:189], v[60:63]
	v_mfma_f32_16x16x32_bf16 v[56:59], v[162:165], v[186:189], v[56:59]
	v_mfma_f32_16x16x32_bf16 v[44:47], v[144:147], v[194:197], v[44:47]
	v_mfma_f32_16x16x32_bf16 v[40:43], v[162:165], v[194:197], v[40:43]
	v_mfma_f32_16x16x32_bf16 v[28:31], v[144:147], v[202:205], v[28:31]
	v_mfma_f32_16x16x32_bf16 v[24:27], v[162:165], v[202:205], v[24:27]
	v_mfma_f32_16x16x32_bf16 v[12:15], v[144:147], v[210:213], v[12:15]
	v_mfma_f32_16x16x32_bf16 v[8:11], v[162:165], v[210:213], v[8:11]
	v_mfma_f32_16x16x32_bf16 v[60:63], v[158:161], v[190:193], v[60:63]
	v_mfma_f32_16x16x32_bf16 v[56:59], v[166:169], v[190:193], v[56:59]
	v_mfma_f32_16x16x32_bf16 v[44:47], v[158:161], v[198:201], v[44:47]
	v_mfma_f32_16x16x32_bf16 v[40:43], v[166:169], v[198:201], v[40:43]
	v_mfma_f32_16x16x32_bf16 v[28:31], v[158:161], v[206:209], v[28:31]
	v_mfma_f32_16x16x32_bf16 v[24:27], v[166:169], v[206:209], v[24:27]
	v_mfma_f32_16x16x32_bf16 v[12:15], v[158:161], v[214:217], v[12:15]
	v_mfma_f32_16x16x32_bf16 v[8:11], v[166:169], v[214:217], v[8:11]
	v_mfma_f32_16x16x32_bf16 v[52:55], v[170:173], v[186:189], v[52:55]
	v_mfma_f32_16x16x32_bf16 v[48:51], v[178:181], v[186:189], v[48:51]
	v_mfma_f32_16x16x32_bf16 v[36:39], v[170:173], v[194:197], v[36:39]
	v_mfma_f32_16x16x32_bf16 v[32:35], v[178:181], v[194:197], v[32:35]
	v_mfma_f32_16x16x32_bf16 v[20:23], v[170:173], v[202:205], v[20:23]
	v_mfma_f32_16x16x32_bf16 v[16:19], v[178:181], v[202:205], v[16:19]
	v_mfma_f32_16x16x32_bf16 v[4:7], v[170:173], v[210:213], v[4:7]
	v_mfma_f32_16x16x32_bf16 v[0:3], v[178:181], v[210:213], v[0:3]
	v_mfma_f32_16x16x32_bf16 v[52:55], v[174:177], v[190:193], v[52:55]
	v_mfma_f32_16x16x32_bf16 v[48:51], v[182:185], v[190:193], v[48:51]
	v_mfma_f32_16x16x32_bf16 v[36:39], v[174:177], v[198:201], v[36:39]
	v_mfma_f32_16x16x32_bf16 v[32:35], v[182:185], v[198:201], v[32:35]
	v_mfma_f32_16x16x32_bf16 v[20:23], v[174:177], v[206:209], v[20:23]
	v_mfma_f32_16x16x32_bf16 v[16:19], v[182:185], v[206:209], v[16:19]
	v_mfma_f32_16x16x32_bf16 v[4:7], v[174:177], v[214:217], v[4:7]
	v_mfma_f32_16x16x32_bf16 v[0:3], v[182:185], v[214:217], v[0:3]
	s_barrier
	s_add_i32 s61, s61, 2
	s_add_u32 s59, s59, 0x100
	s_addc_u32 s60, s60, 0
	s_cmp_gt_u32 s61, 29
	s_mov_b64 s[38:39], s[40:41]
	s_cbranch_scc0 .LBB0_1240
	s_and_b64 vcc, exec, s[6:7]
	s_cbranch_vccz .LBB0_1243
	s_barrier

.LBB0_1327:
	ds_read_b128 v[144:147], v151
	ds_read_b128 v[154:157], v151 offset:1024
	ds_read_b128 v[158:161], v151 offset:2048
	ds_read_b128 v[162:165], v151 offset:3072
	ds_read_b128 v[166:169], v152
	ds_read_b128 v[170:173], v152 offset:1024
	ds_read_b128 v[174:177], v152 offset:2048
	ds_read_b128 v[178:181], v152 offset:3072
	s_add_u32 s34, s30, 0x100
	s_addc_u32 s35, s31, 0
	s_cmpk_eq_i32 s55, 0x54
	s_cselect_b32 s39, s5, s35
	s_cselect_b32 s38, s4, s34
	s_cselect_b32 s37, s29, s54
	s_cselect_b32 s36, s28, s53
	v_lshl_add_u64 v[182:183], s[30:31], 0, v[136:137]
	s_add_i32 m0, s40, 0xc000
	s_nop 0
	global_load_lds_dwordx4 v[182:183], off
	v_lshl_add_u64 v[182:183], s[30:31], 0, v[138:139]
	s_add_i32 m0, s40, 0xe000
	s_nop 0
	global_load_lds_dwordx4 v[182:183], off
	ds_read_b128 v[182:185], v153
	ds_read_b128 v[186:189], v153 offset:1024
	ds_read_b128 v[190:193], v153 offset:2048
	ds_read_b128 v[194:197], v153 offset:3072
	ds_read_b128 v[198:201], v153 offset:4096
	ds_read_b128 v[202:205], v153 offset:5120
	ds_read_b128 v[206:209], v153 offset:6144
	ds_read_b128 v[210:213], v153 offset:7168
	s_waitcnt vmcnt(8)
	s_waitcnt lgkmcnt(0)
	s_barrier
	s_waitcnt lgkmcnt(0)
	v_mfma_f32_16x16x32_bf16 v[124:127], v[144:147], v[182:185], v[124:127]
	v_mfma_f32_16x16x32_bf16 v[120:123], v[158:161], v[182:185], v[120:123]
	v_mfma_f32_16x16x32_bf16 v[108:111], v[144:147], v[190:193], v[108:111]
	v_mfma_f32_16x16x32_bf16 v[104:107], v[158:161], v[190:193], v[104:107]
	v_mfma_f32_16x16x32_bf16 v[92:95], v[144:147], v[198:201], v[92:95]
	v_mfma_f32_16x16x32_bf16 v[88:91], v[158:161], v[198:201], v[88:91]
	v_mfma_f32_16x16x32_bf16 v[76:79], v[144:147], v[206:209], v[76:79]
	v_mfma_f32_16x16x32_bf16 v[72:75], v[158:161], v[206:209], v[72:75]
	v_mfma_f32_16x16x32_bf16 v[124:127], v[154:157], v[186:189], v[124:127]
	v_mfma_f32_16x16x32_bf16 v[120:123], v[162:165], v[186:189], v[120:123]
	v_mfma_f32_16x16x32_bf16 v[108:111], v[154:157], v[194:197], v[108:111]
	v_mfma_f32_16x16x32_bf16 v[104:107], v[162:165], v[194:197], v[104:107]
	v_mfma_f32_16x16x32_bf16 v[92:95], v[154:157], v[202:205], v[92:95]
	v_mfma_f32_16x16x32_bf16 v[88:91], v[162:165], v[202:205], v[88:91]
	v_mfma_f32_16x16x32_bf16 v[76:79], v[154:157], v[210:213], v[76:79]
	v_mfma_f32_16x16x32_bf16 v[72:75], v[162:165], v[210:213], v[72:75]
	v_mfma_f32_16x16x32_bf16 v[116:119], v[166:169], v[182:185], v[116:119]
	v_mfma_f32_16x16x32_bf16 v[112:115], v[174:177], v[182:185], v[112:115]
	v_mfma_f32_16x16x32_bf16 v[100:103], v[166:169], v[190:193], v[100:103]
	v_mfma_f32_16x16x32_bf16 v[96:99], v[174:177], v[190:193], v[96:99]
	v_mfma_f32_16x16x32_bf16 v[84:87], v[166:169], v[198:201], v[84:87]
	v_mfma_f32_16x16x32_bf16 v[80:83], v[174:177], v[198:201], v[80:83]
	v_mfma_f32_16x16x32_bf16 v[68:71], v[166:169], v[206:209], v[68:71]
	v_mfma_f32_16x16x32_bf16 v[64:67], v[174:177], v[206:209], v[64:67]
	v_mfma_f32_16x16x32_bf16 v[116:119], v[170:173], v[186:189], v[116:119]
	v_mfma_f32_16x16x32_bf16 v[112:115], v[178:181], v[186:189], v[112:115]
	v_mfma_f32_16x16x32_bf16 v[100:103], v[170:173], v[194:197], v[100:103]
	v_mfma_f32_16x16x32_bf16 v[96:99], v[178:181], v[194:197], v[96:99]
	v_mfma_f32_16x16x32_bf16 v[84:87], v[170:173], v[202:205], v[84:87]
	v_mfma_f32_16x16x32_bf16 v[80:83], v[178:181], v[202:205], v[80:83]
	v_mfma_f32_16x16x32_bf16 v[68:71], v[170:173], v[210:213], v[68:71]
	v_mfma_f32_16x16x32_bf16 v[64:67], v[178:181], v[210:213], v[64:67]
	s_barrier
	s_add_i32 s30, s48, s23
	v_lshl_add_u64 v[214:215], s[36:37], 0, v[130:131]
	s_mov_b32 m0, s30
	v_lshl_add_u64 v[216:217], s[36:37], 0, v[134:135]
	global_load_lds_dwordx4 v[214:215], off
	s_add_i32 m0, s30, 0x2000
	s_add_u32 s30, s36, 0x160000
	s_addc_u32 s31, s37, 0
	s_add_i32 s56, s49, s23
	global_load_lds_dwordx4 v[216:217], off
	v_lshl_add_u64 v[182:183], s[30:31], 0, v[130:131]
	s_mov_b32 m0, s56
	v_lshl_add_u64 v[218:219], s[38:39], 0, v[128:129]
	global_load_lds_dwordx4 v[182:183], off
	v_lshl_add_u64 v[182:183], s[30:31], 0, v[134:135]
	s_add_i32 m0, s56, 0x2000
	v_lshl_add_u64 v[220:221], s[38:39], 0, v[132:133]
	global_load_lds_dwordx4 v[182:183], off
	s_mov_b32 m0, s40
	s_nop 0
	global_load_lds_dwordx4 v[218:219], off
	s_mov_b32 m0, s41
	s_nop 0
	global_load_lds_dwordx4 v[220:221], off
	ds_read_b128 v[182:185], v153 offset:16384
	ds_read_b128 v[186:189], v153 offset:17408
	ds_read_b128 v[190:193], v153 offset:18432
	ds_read_b128 v[194:197], v153 offset:19456
	ds_read_b128 v[198:201], v153 offset:20480
	ds_read_b128 v[202:205], v153 offset:21504
	ds_read_b128 v[206:209], v153 offset:22528
	ds_read_b128 v[210:213], v153 offset:23552
	s_waitcnt vmcnt(8)
	s_waitcnt lgkmcnt(0)
	s_barrier
	s_waitcnt lgkmcnt(0)
	v_mfma_f32_16x16x32_bf16 v[60:63], v[144:147], v[182:185], v[60:63]
	v_mfma_f32_16x16x32_bf16 v[56:59], v[158:161], v[182:185], v[56:59]
	v_mfma_f32_16x16x32_bf16 v[44:47], v[144:147], v[190:193], v[44:47]
	v_mfma_f32_16x16x32_bf16 v[40:43], v[158:161], v[190:193], v[40:43]
	v_mfma_f32_16x16x32_bf16 v[28:31], v[144:147], v[198:201], v[28:31]
	v_mfma_f32_16x16x32_bf16 v[24:27], v[158:161], v[198:201], v[24:27]
	v_mfma_f32_16x16x32_bf16 v[12:15], v[144:147], v[206:209], v[12:15]
	v_mfma_f32_16x16x32_bf16 v[8:11], v[158:161], v[206:209], v[8:11]
	v_mfma_f32_16x16x32_bf16 v[60:63], v[154:157], v[186:189], v[60:63]
	v_mfma_f32_16x16x32_bf16 v[56:59], v[162:165], v[186:189], v[56:59]
	v_mfma_f32_16x16x32_bf16 v[44:47], v[154:157], v[194:197], v[44:47]
	v_mfma_f32_16x16x32_bf16 v[40:43], v[162:165], v[194:197], v[40:43]
	v_mfma_f32_16x16x32_bf16 v[28:31], v[154:157], v[202:205], v[28:31]
	v_mfma_f32_16x16x32_bf16 v[24:27], v[162:165], v[202:205], v[24:27]
	v_mfma_f32_16x16x32_bf16 v[12:15], v[154:157], v[210:213], v[12:15]
	v_mfma_f32_16x16x32_bf16 v[8:11], v[162:165], v[210:213], v[8:11]
	v_mfma_f32_16x16x32_bf16 v[52:55], v[166:169], v[182:185], v[52:55]
	v_mfma_f32_16x16x32_bf16 v[48:51], v[174:177], v[182:185], v[48:51]
	v_mfma_f32_16x16x32_bf16 v[36:39], v[166:169], v[190:193], v[36:39]
	v_mfma_f32_16x16x32_bf16 v[32:35], v[174:177], v[190:193], v[32:35]
	v_mfma_f32_16x16x32_bf16 v[20:23], v[166:169], v[198:201], v[20:23]
	v_mfma_f32_16x16x32_bf16 v[16:19], v[174:177], v[198:201], v[16:19]
	v_mfma_f32_16x16x32_bf16 v[4:7], v[166:169], v[206:209], v[4:7]
	v_mfma_f32_16x16x32_bf16 v[0:3], v[174:177], v[206:209], v[0:3]
	v_mfma_f32_16x16x32_bf16 v[52:55], v[170:173], v[186:189], v[52:55]
	v_mfma_f32_16x16x32_bf16 v[48:51], v[178:181], v[186:189], v[48:51]
	v_mfma_f32_16x16x32_bf16 v[36:39], v[170:173], v[194:197], v[36:39]
	v_mfma_f32_16x16x32_bf16 v[32:35], v[178:181], v[194:197], v[32:35]
	v_mfma_f32_16x16x32_bf16 v[20:23], v[170:173], v[202:205], v[20:23]
	v_mfma_f32_16x16x32_bf16 v[16:19], v[178:181], v[202:205], v[16:19]
	v_mfma_f32_16x16x32_bf16 v[4:7], v[170:173], v[210:213], v[4:7]
	v_mfma_f32_16x16x32_bf16 v[0:3], v[178:181], v[210:213], v[0:3]
	s_barrier
	s_add_i32 s56, 0, 0x18000
	s_add_i32 s57, 0, 0x1c000
	v_add_u32_e32 v162, s56, v148
	v_add_u32_e32 v178, s57, v148
	ds_read_b128 v[144:147], v162
	ds_read_b128 v[154:157], v162 offset:1024
	ds_read_b128 v[158:161], v162 offset:2048
	ds_read_b128 v[162:165], v162 offset:3072
	ds_read_b128 v[166:169], v178
	ds_read_b128 v[170:173], v178 offset:1024
	ds_read_b128 v[174:177], v178 offset:2048
	ds_read_b128 v[178:181], v178 offset:3072
	s_add_u32 s30, s38, 0x160000
	s_addc_u32 s31, s39, 0
	s_mov_b32 m0, s42
	v_lshl_add_u64 v[182:183], s[30:31], 0, v[128:129]
	global_load_lds_dwordx4 v[182:183], off
	v_lshl_add_u64 v[182:183], s[30:31], 0, v[132:133]
	s_mov_b32 m0, s43
	s_nop 0
	global_load_lds_dwordx4 v[182:183], off
	ds_read_b128 v[182:185], v153 offset:32768
	ds_read_b128 v[186:189], v153 offset:33792
	ds_read_b128 v[190:193], v153 offset:34816
	ds_read_b128 v[194:197], v153 offset:35840
	ds_read_b128 v[198:201], v153 offset:36864
	ds_read_b128 v[202:205], v153 offset:37888
	ds_read_b128 v[206:209], v153 offset:38912
	ds_read_b128 v[210:213], v153 offset:39936
	s_waitcnt vmcnt(8)
	s_waitcnt lgkmcnt(0)
	s_barrier
	s_waitcnt lgkmcnt(0)
	v_mfma_f32_16x16x32_bf16 v[124:127], v[144:147], v[182:185], v[124:127]
	v_mfma_f32_16x16x32_bf16 v[120:123], v[158:161], v[182:185], v[120:123]
	v_mfma_f32_16x16x32_bf16 v[108:111], v[144:147], v[190:193], v[108:111]
	v_mfma_f32_16x16x32_bf16 v[104:107], v[158:161], v[190:193], v[104:107]
	v_mfma_f32_16x16x32_bf16 v[92:95], v[144:147], v[198:201], v[92:95]
	v_mfma_f32_16x16x32_bf16 v[88:91], v[158:161], v[198:201], v[88:91]
	v_mfma_f32_16x16x32_bf16 v[76:79], v[144:147], v[206:209], v[76:79]
	v_mfma_f32_16x16x32_bf16 v[72:75], v[158:161], v[206:209], v[72:75]
	v_mfma_f32_16x16x32_bf16 v[124:127], v[154:157], v[186:189], v[124:127]
	v_mfma_f32_16x16x32_bf16 v[120:123], v[162:165], v[186:189], v[120:123]
	v_mfma_f32_16x16x32_bf16 v[108:111], v[154:157], v[194:197], v[108:111]
	v_mfma_f32_16x16x32_bf16 v[104:107], v[162:165], v[194:197], v[104:107]
	v_mfma_f32_16x16x32_bf16 v[92:95], v[154:157], v[202:205], v[92:95]
	v_mfma_f32_16x16x32_bf16 v[88:91], v[162:165], v[202:205], v[88:91]
	v_mfma_f32_16x16x32_bf16 v[76:79], v[154:157], v[210:213], v[76:79]
	v_mfma_f32_16x16x32_bf16 v[72:75], v[162:165], v[210:213], v[72:75]
	v_mfma_f32_16x16x32_bf16 v[116:119], v[166:169], v[182:185], v[116:119]
	v_mfma_f32_16x16x32_bf16 v[112:115], v[174:177], v[182:185], v[112:115]
	v_mfma_f32_16x16x32_bf16 v[100:103], v[166:169], v[190:193], v[100:103]
	v_mfma_f32_16x16x32_bf16 v[96:99], v[174:177], v[190:193], v[96:99]
	v_mfma_f32_16x16x32_bf16 v[84:87], v[166:169], v[198:201], v[84:87]
	v_mfma_f32_16x16x32_bf16 v[80:83], v[174:177], v[198:201], v[80:83]
	v_mfma_f32_16x16x32_bf16 v[68:71], v[166:169], v[206:209], v[68:71]
	v_mfma_f32_16x16x32_bf16 v[64:67], v[174:177], v[206:209], v[64:67]
	v_mfma_f32_16x16x32_bf16 v[116:119], v[170:173], v[186:189], v[116:119]
	v_mfma_f32_16x16x32_bf16 v[112:115], v[178:181], v[186:189], v[112:115]
	v_mfma_f32_16x16x32_bf16 v[100:103], v[170:173], v[194:197], v[100:103]
	v_mfma_f32_16x16x32_bf16 v[96:99], v[178:181], v[194:197], v[96:99]
	v_mfma_f32_16x16x32_bf16 v[84:87], v[170:173], v[202:205], v[84:87]
	v_mfma_f32_16x16x32_bf16 v[80:83], v[178:181], v[202:205], v[80:83]
	v_mfma_f32_16x16x32_bf16 v[68:71], v[170:173], v[210:213], v[68:71]
	v_mfma_f32_16x16x32_bf16 v[64:67], v[178:181], v[210:213], v[64:67]
	s_barrier
	s_add_i32 s30, s56, s23
	v_lshl_add_u64 v[182:183], v[214:215], 0, s[16:17]
	s_mov_b32 m0, s30
	s_nop 0
	global_load_lds_dwordx4 v[182:183], off
	s_add_i32 m0, s30, 0x2000
	s_add_u32 s30, s36, 0x160080
	v_lshl_add_u64 v[182:183], v[216:217], 0, s[16:17]
	s_addc_u32 s31, s37, 0
	s_add_i32 s36, s57, s23
	global_load_lds_dwordx4 v[182:183], off
	v_lshl_add_u64 v[182:183], s[30:31], 0, v[130:131]
	s_mov_b32 m0, s36
	s_nop 0
	global_load_lds_dwordx4 v[182:183], off
	v_lshl_add_u64 v[182:183], s[30:31], 0, v[134:135]
	s_add_i32 m0, s36, 0x2000
	s_nop 0
	global_load_lds_dwordx4 v[182:183], off
	v_lshl_add_u64 v[182:183], v[218:219], 0, s[16:17]
	s_mov_b32 m0, s45
	s_nop 0
	global_load_lds_dwordx4 v[182:183], off
	v_lshl_add_u64 v[182:183], v[220:221], 0, s[16:17]
	s_mov_b32 m0, s46
	s_nop 0
	global_load_lds_dwordx4 v[182:183], off
	ds_read_b128 v[182:185], v153 offset:49152
	ds_read_b128 v[186:189], v153 offset:50176
	ds_read_b128 v[190:193], v153 offset:51200
	ds_read_b128 v[194:197], v153 offset:52224
	ds_read_b128 v[198:201], v153 offset:53248
	ds_read_b128 v[202:205], v153 offset:54272
	ds_read_b128 v[206:209], v153 offset:55296
	ds_read_b128 v[210:213], v153 offset:56320
	s_waitcnt vmcnt(8)
	s_waitcnt lgkmcnt(0)
	s_barrier
	s_waitcnt lgkmcnt(0)
	v_mfma_f32_16x16x32_bf16 v[60:63], v[144:147], v[182:185], v[60:63]
	v_mfma_f32_16x16x32_bf16 v[56:59], v[158:161], v[182:185], v[56:59]
	v_mfma_f32_16x16x32_bf16 v[44:47], v[144:147], v[190:193], v[44:47]
	v_mfma_f32_16x16x32_bf16 v[40:43], v[158:161], v[190:193], v[40:43]
	v_mfma_f32_16x16x32_bf16 v[28:31], v[144:147], v[198:201], v[28:31]
	v_mfma_f32_16x16x32_bf16 v[24:27], v[158:161], v[198:201], v[24:27]
	v_mfma_f32_16x16x32_bf16 v[12:15], v[144:147], v[206:209], v[12:15]
	v_mfma_f32_16x16x32_bf16 v[8:11], v[158:161], v[206:209], v[8:11]
	v_mfma_f32_16x16x32_bf16 v[60:63], v[154:157], v[186:189], v[60:63]
	v_mfma_f32_16x16x32_bf16 v[56:59], v[162:165], v[186:189], v[56:59]
	v_mfma_f32_16x16x32_bf16 v[44:47], v[154:157], v[194:197], v[44:47]
	v_mfma_f32_16x16x32_bf16 v[40:43], v[162:165], v[194:197], v[40:43]
	v_mfma_f32_16x16x32_bf16 v[28:31], v[154:157], v[202:205], v[28:31]
	v_mfma_f32_16x16x32_bf16 v[24:27], v[162:165], v[202:205], v[24:27]
	v_mfma_f32_16x16x32_bf16 v[12:15], v[154:157], v[210:213], v[12:15]
	v_mfma_f32_16x16x32_bf16 v[8:11], v[162:165], v[210:213], v[8:11]
	v_mfma_f32_16x16x32_bf16 v[52:55], v[166:169], v[182:185], v[52:55]
	v_mfma_f32_16x16x32_bf16 v[48:51], v[174:177], v[182:185], v[48:51]
	v_mfma_f32_16x16x32_bf16 v[36:39], v[166:169], v[190:193], v[36:39]
	v_mfma_f32_16x16x32_bf16 v[32:35], v[174:177], v[190:193], v[32:35]
	v_mfma_f32_16x16x32_bf16 v[20:23], v[166:169], v[198:201], v[20:23]
	v_mfma_f32_16x16x32_bf16 v[16:19], v[174:177], v[198:201], v[16:19]
	v_mfma_f32_16x16x32_bf16 v[4:7], v[166:169], v[206:209], v[4:7]
	v_mfma_f32_16x16x32_bf16 v[0:3], v[174:177], v[206:209], v[0:3]
	v_mfma_f32_16x16x32_bf16 v[52:55], v[170:173], v[186:189], v[52:55]
	v_mfma_f32_16x16x32_bf16 v[48:51], v[178:181], v[186:189], v[48:51]
	v_mfma_f32_16x16x32_bf16 v[36:39], v[170:173], v[194:197], v[36:39]
	v_mfma_f32_16x16x32_bf16 v[32:35], v[178:181], v[194:197], v[32:35]
	v_mfma_f32_16x16x32_bf16 v[20:23], v[170:173], v[202:205], v[20:23]
	v_mfma_f32_16x16x32_bf16 v[16:19], v[178:181], v[202:205], v[16:19]
	v_mfma_f32_16x16x32_bf16 v[4:7], v[170:173], v[210:213], v[4:7]
	v_mfma_f32_16x16x32_bf16 v[0:3], v[178:181], v[210:213], v[0:3]
	s_barrier
	s_add_i32 s55, s55, 2
	s_add_u32 s53, s53, 0x100
	s_addc_u32 s54, s54, 0
	s_cmpk_gt_u32 s55, 0x55
	s_mov_b64 s[30:31], s[34:35]
	s_cbranch_scc0 .LBB0_1327
	s_and_b64 vcc, exec, s[8:9]
	s_cbranch_vccz .LBB0_1330
	s_barrier
